# on top of best: K-loop heads issue the 16 fragment reads before the scalar pointer math; tail updates moved under the last MFMA block
# speedup vs baseline: 1.0144x; 1.0116x over previous
; #define PG8_STAGE(bufoff, gbase, voff) do { _Pragma("unroll") for (int _i = 0; _i < 2; ++_i) \
;         __builtin_amdgcn_global_load_lds((const unsigned*)((const char*)(gbase) + (voff)[_i]), (PG8_LAS unsigned*)(lds + (bufoff) + ldsw + _i * 8192), 16, 0, 0); } while (0)
; #define PG8_LDA(dst, b, h) do { _Pragma("unroll") for (int m = 0; m < 4; ++m) _Pragma("unroll") for (int k = 0; k < 2; ++k) dst[m][k] = *(const PG8_LAS bf16x8*)(lds + PG8_SA(b, h) + aoff + m * 2048 + k * 1024); } while (0)
; #define PG8_LDB(dst, b, h) do { _Pragma("unroll") for (int n = 0; n < 2; ++n) _Pragma("unroll") for (int k = 0; k < 2; ++k) dst[n][k] = *(const PG8_LAS bf16x8*)(lds + PG8_SB(b, h) + boff + n * 2048 + k * 1024); } while (0)
; #define PG8_MMA(ai, bj, At, Bt) do { __builtin_amdgcn_s_setprio(1); _Pragma("unroll") for (int m = 0; m < 4; ++m) _Pragma("unroll") for (int n = 0; n < 2; ++n) _Pragma("unroll") for (int k = 0; k < 2; ++k) \
;         acc[ai][bj][m][n] = __builtin_amdgcn_mfma_f32_16x16x32_bf16(Bt[n][k], At[m][k], acc[ai][bj][m][n], 0, 0, 0); __builtin_amdgcn_s_setprio(0); } while (0)
; #define PG8_WAIT_V(n) asm volatile("s_waitcnt vmcnt(" #n ")" ::: "memory")
; #define PG8_WAIT_L(n) asm volatile("s_waitcnt lgkmcnt(" #n ")" ::: "memory")
; template <class Epi, class Sched, bool ALIGN_EPI = false, bool SP2 = false>
; __device__ __forceinline__ void gemm_phase(PG8_LAS unsigned char* lds, const Gemm g, const Sched& S, const Epi& E) {
;     ...
;             const bool last = (t == nt - 2);
;             const char* a1 = cA + (size_t)(t + 1) * kstep;
;             const char* a2 = last ? nA : cA + (size_t)(t + 2) * kstep; const char* b2 = last ? nB : cB + (size_t)(t + 2) * kstep;
;             const char* a3 = a2 + kstep; const char* b3 = b2 + kstep;
;             if (last && has_next) S.a_ready(nxt);
;             if constexpr (SP2) {
;             PG8_LDB(B0, 0, 0); PG8_LDB(B1, 0, 1); PG8_SCHED; PG8_LDA(At, 0, 0); PG8_STAGE(PG8_SA(1, 1), a1 + hstep, voffA);
;             PG8_WAIT_V(8); PG8_WAIT_L(0); PG8_BAR; PG8_MMA(0, 0, At, B0); PG8_MMA(0, 1, At, B1); PG8_BAR; PG8_SCHED;
;             PG8_LDA(At, 0, 1); PG8_STAGE(PG8_SB(0, 0), b2, voffB); PG8_STAGE(PG8_SB(0, 1), b2 + hstep, voffB); PG8_STAGE(PG8_SA(0, 0), a2, voffA);
;             PG8_WAIT_V(8); PG8_WAIT_L(0); PG8_BAR; PG8_MMA(1, 0, At, B0); PG8_MMA(1, 1, At, B1); PG8_BAR; PG8_SCHED;
.LBB0_132:
	s_add_i32 s39, 0, 0x10000
	v_add_u32_e32 v0, s39, v176
	s_add_i32 s18, 0, 0x14000
	ds_read_b128 v[144:147], v0
	ds_read_b128 v[148:151], v0 offset:1024
	ds_read_b128 v[152:155], v0 offset:2048
	ds_read_b128 v[156:159], v0 offset:3072
	v_add_u32_e32 v0, s18, v176
	ds_read_b128 v[160:163], v0
	ds_read_b128 v[164:167], v0 offset:1024
	ds_read_b128 v[168:171], v0 offset:2048
	ds_read_b128 v[172:175], v0 offset:3072
	ds_read_b128 v[180:183], v178
	ds_read_b128 v[184:187], v178 offset:1024
	ds_read_b128 v[188:191], v178 offset:2048
	ds_read_b128 v[192:195], v178 offset:3072
	ds_read_b128 v[202:205], v178 offset:4096
	ds_read_b128 v[206:209], v178 offset:5120
	ds_read_b128 v[210:213], v178 offset:6144
	ds_read_b128 v[214:217], v178 offset:7168
	s_add_u32 s100, s46, 0xfffc0080
	s_addc_u32 s101, s47, -1
	s_cmp_eq_u32 s85, 12
	s_cselect_b32 s81, s33, s101
	s_cselect_b32 s80, s73, s100
	s_cselect_b32 s45, s75, s84
	s_cselect_b32 s44, s82, s83
	s_add_i32 m0, s92, 0xc000
	v_lshl_add_u64 v[218:219], s[46:47], 0, v[140:141]
	global_load_lds_dwordx4 v[218:219], off
	v_lshl_add_u64 v[218:219], s[46:47], 0, v[142:143]
	s_add_i32 m0, s92, 0xe000
	s_nop 0
	global_load_lds_dwordx4 v[218:219], off
	s_waitcnt vmcnt(8)
	s_waitcnt lgkmcnt(0)
	s_barrier
	s_setprio 1
	v_mfma_f32_16x16x32_bf16 v[118:121], v[144:147], v[180:183], v[118:121]
	v_mfma_f32_16x16x32_bf16 v[118:121], v[148:151], v[184:187], v[118:121]
	v_mfma_f32_16x16x32_bf16 v[102:105], v[144:147], v[188:191], v[102:105]
	v_mfma_f32_16x16x32_bf16 v[102:105], v[148:151], v[192:195], v[102:105]
	v_mfma_f32_16x16x32_bf16 v[86:89], v[144:147], v[202:205], v[86:89]
	v_mfma_f32_16x16x32_bf16 v[86:89], v[148:151], v[206:209], v[86:89]
	v_mfma_f32_16x16x32_bf16 v[70:73], v[144:147], v[210:213], v[70:73]
	v_mfma_f32_16x16x32_bf16 v[70:73], v[148:151], v[214:217], v[70:73]
	v_mfma_f32_16x16x32_bf16 v[114:117], v[152:155], v[180:183], v[114:117]
	v_mfma_f32_16x16x32_bf16 v[114:117], v[156:159], v[184:187], v[114:117]
	v_mfma_f32_16x16x32_bf16 v[98:101], v[152:155], v[188:191], v[98:101]
	v_mfma_f32_16x16x32_bf16 v[98:101], v[156:159], v[192:195], v[98:101]
	v_mfma_f32_16x16x32_bf16 v[82:85], v[152:155], v[202:205], v[82:85]
	v_mfma_f32_16x16x32_bf16 v[82:85], v[156:159], v[206:209], v[82:85]
	v_mfma_f32_16x16x32_bf16 v[66:69], v[152:155], v[210:213], v[66:69]
	v_mfma_f32_16x16x32_bf16 v[66:69], v[156:159], v[214:217], v[66:69]
	v_mfma_f32_16x16x32_bf16 v[126:129], v[160:163], v[180:183], v[126:129]
	v_mfma_f32_16x16x32_bf16 v[126:129], v[164:167], v[184:187], v[126:129]
	v_mfma_f32_16x16x32_bf16 v[110:113], v[160:163], v[188:191], v[110:113]
	v_mfma_f32_16x16x32_bf16 v[110:113], v[164:167], v[192:195], v[110:113]
	v_mfma_f32_16x16x32_bf16 v[94:97], v[160:163], v[202:205], v[94:97]
	v_mfma_f32_16x16x32_bf16 v[94:97], v[164:167], v[206:209], v[94:97]
	v_mfma_f32_16x16x32_bf16 v[78:81], v[160:163], v[210:213], v[78:81]
	v_mfma_f32_16x16x32_bf16 v[78:81], v[164:167], v[214:217], v[78:81]
	v_mfma_f32_16x16x32_bf16 v[122:125], v[168:171], v[180:183], v[122:125]
	v_mfma_f32_16x16x32_bf16 v[122:125], v[172:175], v[184:187], v[122:125]
	v_mfma_f32_16x16x32_bf16 v[106:109], v[168:171], v[188:191], v[106:109]
	v_mfma_f32_16x16x32_bf16 v[106:109], v[172:175], v[192:195], v[106:109]
	v_mfma_f32_16x16x32_bf16 v[90:93], v[168:171], v[202:205], v[90:93]
	v_mfma_f32_16x16x32_bf16 v[90:93], v[172:175], v[206:209], v[90:93]
	v_mfma_f32_16x16x32_bf16 v[74:77], v[168:171], v[210:213], v[74:77]
	v_mfma_f32_16x16x32_bf16 v[74:77], v[172:175], v[214:217], v[74:77]
	s_setprio 0
	s_barrier
	s_add_i32 s38, s39, s91
	v_lshl_add_u64 v[218:219], s[44:45], 0, v[134:135]
	s_mov_b32 m0, s38
	ds_read_b128 v[180:183], v178 offset:16384
	ds_read_b128 v[184:187], v178 offset:17408
	ds_read_b128 v[188:191], v178 offset:18432
	ds_read_b128 v[192:195], v178 offset:19456
	ds_read_b128 v[202:205], v178 offset:20480
	ds_read_b128 v[206:209], v178 offset:21504
	ds_read_b128 v[210:213], v178 offset:22528
	ds_read_b128 v[214:217], v178 offset:23552
	global_load_lds_dwordx4 v[218:219], off
	s_add_i32 m0, s38, 0x2000
	s_add_u32 s38, s44, 0x40000
	v_lshl_add_u64 v[220:221], s[44:45], 0, v[130:131]
	s_addc_u32 s39, s45, 0
	s_add_i32 s18, s18, s91
	global_load_lds_dwordx4 v[220:221], off
	v_lshl_add_u64 v[222:223], s[38:39], 0, v[134:135]
	s_mov_b32 m0, s18
	v_lshl_add_u64 v[224:225], s[80:81], 0, v[132:133]
	global_load_lds_dwordx4 v[222:223], off
	v_lshl_add_u64 v[222:223], s[38:39], 0, v[130:131]
	s_add_i32 m0, s18, 0x2000
	s_nop 0
	global_load_lds_dwordx4 v[222:223], off
	v_lshl_add_u64 v[222:223], s[80:81], 0, v[136:137]
	s_mov_b32 m0, s92
	s_nop 0
	global_load_lds_dwordx4 v[222:223], off
	s_mov_b32 m0, s93
	s_nop 0
	global_load_lds_dwordx4 v[224:225], off
	s_waitcnt vmcnt(8)
	s_waitcnt lgkmcnt(0)
	s_barrier
; #define PG8_STAGE(bufoff, gbase, voff) do { _Pragma("unroll") for (int _i = 0; _i < 2; ++_i) \
;         __builtin_amdgcn_global_load_lds((const unsigned*)((const char*)(gbase) + (voff)[_i]), (PG8_LAS unsigned*)(lds + (bufoff) + ldsw + _i * 8192), 16, 0, 0); } while (0)
; #define PG8_LDA(dst, b, h) do { _Pragma("unroll") for (int m = 0; m < 4; ++m) _Pragma("unroll") for (int k = 0; k < 2; ++k) dst[m][k] = *(const PG8_LAS bf16x8*)(lds + PG8_SA(b, h) + aoff + m * 2048 + k * 1024); } while (0)
; #define PG8_LDB(dst, b, h) do { _Pragma("unroll") for (int n = 0; n < 2; ++n) _Pragma("unroll") for (int k = 0; k < 2; ++k) dst[n][k] = *(const PG8_LAS bf16x8*)(lds + PG8_SB(b, h) + boff + n * 2048 + k * 1024); } while (0)
; #define PG8_MMA(ai, bj, At, Bt) do { __builtin_amdgcn_s_setprio(1); _Pragma("unroll") for (int m = 0; m < 4; ++m) _Pragma("unroll") for (int n = 0; n < 2; ++n) _Pragma("unroll") for (int k = 0; k < 2; ++k) \
;         acc[ai][bj][m][n] = __builtin_amdgcn_mfma_f32_16x16x32_bf16(Bt[n][k], At[m][k], acc[ai][bj][m][n], 0, 0, 0); __builtin_amdgcn_s_setprio(0); } while (0)
; #define PG8_WAIT_V(n) asm volatile("s_waitcnt vmcnt(" #n ")" ::: "memory")
; #define PG8_WAIT_L(n) asm volatile("s_waitcnt lgkmcnt(" #n ")" ::: "memory")
; #define PG8_BAR __builtin_amdgcn_s_barrier()
; #define PG8_SCHED __builtin_amdgcn_sched_barrier(0)
; template <class Epi, class Sched, bool ALIGN_EPI = false, bool SP2 = false>
; __device__ __forceinline__ void gemm_phase(PG8_LAS unsigned char* lds, const Gemm g, const Sched& S, const Epi& E) {
;     ...
;             PG8_WAIT_V(8); PG8_WAIT_L(0); PG8_BAR; PG8_MMA(1, 0, At, B0); PG8_MMA(1, 1, At, B1); PG8_BAR; PG8_SCHED;
;             PG8_LDB(B0, 1, 0); PG8_LDB(B1, 1, 1); PG8_SCHED; PG8_LDA(At, 1, 0); PG8_STAGE(PG8_SA(0, 1), a2 + hstep, voffA);
;             PG8_WAIT_V(8); PG8_WAIT_L(0); PG8_BAR; PG8_MMA(0, 0, At, B0); PG8_MMA(0, 1, At, B1); PG8_BAR; PG8_SCHED;
	s_setprio 1
	v_mfma_f32_16x16x32_bf16 v[54:57], v[144:147], v[180:183], v[54:57]
	v_mfma_f32_16x16x32_bf16 v[54:57], v[148:151], v[184:187], v[54:57]
	v_mfma_f32_16x16x32_bf16 v[38:41], v[144:147], v[188:191], v[38:41]
	v_mfma_f32_16x16x32_bf16 v[38:41], v[148:151], v[192:195], v[38:41]
	v_mfma_f32_16x16x32_bf16 v[22:25], v[144:147], v[202:205], v[22:25]
	v_mfma_f32_16x16x32_bf16 v[22:25], v[148:151], v[206:209], v[22:25]
	v_mfma_f32_16x16x32_bf16 v[6:9], v[144:147], v[210:213], v[6:9]
	v_mfma_f32_16x16x32_bf16 v[6:9], v[148:151], v[214:217], v[6:9]
	v_mfma_f32_16x16x32_bf16 v[50:53], v[152:155], v[180:183], v[50:53]
	v_mfma_f32_16x16x32_bf16 v[50:53], v[156:159], v[184:187], v[50:53]
	v_mfma_f32_16x16x32_bf16 v[34:37], v[152:155], v[188:191], v[34:37]
	v_mfma_f32_16x16x32_bf16 v[34:37], v[156:159], v[192:195], v[34:37]
	v_mfma_f32_16x16x32_bf16 v[18:21], v[152:155], v[202:205], v[18:21]
	v_mfma_f32_16x16x32_bf16 v[18:21], v[156:159], v[206:209], v[18:21]
	v_mfma_f32_16x16x32_bf16 v[2:5], v[152:155], v[210:213], v[2:5]
	v_mfma_f32_16x16x32_bf16 v[2:5], v[156:159], v[214:217], v[2:5]
	v_mfma_f32_16x16x32_bf16 v[62:65], v[160:163], v[180:183], v[62:65]
	v_mfma_f32_16x16x32_bf16 v[62:65], v[164:167], v[184:187], v[62:65]
	v_mfma_f32_16x16x32_bf16 v[46:49], v[160:163], v[188:191], v[46:49]
	v_mfma_f32_16x16x32_bf16 v[46:49], v[164:167], v[192:195], v[46:49]
	v_mfma_f32_16x16x32_bf16 v[30:33], v[160:163], v[202:205], v[30:33]
	v_mfma_f32_16x16x32_bf16 v[30:33], v[164:167], v[206:209], v[30:33]
	v_mfma_f32_16x16x32_bf16 v[10:13], v[160:163], v[210:213], v[10:13]
	v_mfma_f32_16x16x32_bf16 v[10:13], v[164:167], v[214:217], v[10:13]
	v_mfma_f32_16x16x32_bf16 v[58:61], v[168:171], v[180:183], v[58:61]
	v_mfma_f32_16x16x32_bf16 v[58:61], v[172:175], v[184:187], v[58:61]
	v_mfma_f32_16x16x32_bf16 v[42:45], v[168:171], v[188:191], v[42:45]
	v_mfma_f32_16x16x32_bf16 v[42:45], v[172:175], v[192:195], v[42:45]
	v_mfma_f32_16x16x32_bf16 v[26:29], v[168:171], v[202:205], v[26:29]
	v_mfma_f32_16x16x32_bf16 v[26:29], v[172:175], v[206:209], v[26:29]
	v_mfma_f32_16x16x32_bf16 v[14:17], v[168:171], v[210:213], v[14:17]
	v_mfma_f32_16x16x32_bf16 v[14:17], v[172:175], v[214:217], v[14:17]
	s_setprio 0
	s_barrier
	s_add_i32 s18, 0, 0x18000
	v_add_u32_e32 v0, s18, v176
	s_add_i32 vcc_lo, 0, 0x1c000
	ds_read_b128 v[144:147], v0
	ds_read_b128 v[148:151], v0 offset:1024
	ds_read_b128 v[152:155], v0 offset:2048
	ds_read_b128 v[156:159], v0 offset:3072
	v_add_u32_e32 v0, vcc_lo, v176
	ds_read_b128 v[160:163], v0
	ds_read_b128 v[164:167], v0 offset:1024
	ds_read_b128 v[168:171], v0 offset:2048
	ds_read_b128 v[172:175], v0 offset:3072
	s_add_u32 s38, s80, 0x40000
	s_addc_u32 s39, s81, 0
	s_mov_b32 m0, s94
	v_lshl_add_u64 v[226:227], s[38:39], 0, v[136:137]
	ds_read_b128 v[180:183], v178 offset:32768
	ds_read_b128 v[184:187], v178 offset:33792
	ds_read_b128 v[188:191], v178 offset:34816
	ds_read_b128 v[192:195], v178 offset:35840
	ds_read_b128 v[202:205], v178 offset:36864
	ds_read_b128 v[206:209], v178 offset:37888
	ds_read_b128 v[210:213], v178 offset:38912
	ds_read_b128 v[214:217], v178 offset:39936
	global_load_lds_dwordx4 v[226:227], off
	v_lshl_add_u64 v[226:227], s[38:39], 0, v[132:133]
	s_mov_b32 m0, s95
	s_nop 0
	global_load_lds_dwordx4 v[226:227], off
	s_waitcnt vmcnt(8)
	s_waitcnt lgkmcnt(0)
	s_barrier
	s_setprio 1
	v_mfma_f32_16x16x32_bf16 v[118:121], v[144:147], v[180:183], v[118:121]
	v_mfma_f32_16x16x32_bf16 v[118:121], v[148:151], v[184:187], v[118:121]
	v_mfma_f32_16x16x32_bf16 v[102:105], v[144:147], v[188:191], v[102:105]
	v_mfma_f32_16x16x32_bf16 v[102:105], v[148:151], v[192:195], v[102:105]
	v_mfma_f32_16x16x32_bf16 v[86:89], v[144:147], v[202:205], v[86:89]
	v_mfma_f32_16x16x32_bf16 v[86:89], v[148:151], v[206:209], v[86:89]
	v_mfma_f32_16x16x32_bf16 v[70:73], v[144:147], v[210:213], v[70:73]
	v_mfma_f32_16x16x32_bf16 v[70:73], v[148:151], v[214:217], v[70:73]
	v_mfma_f32_16x16x32_bf16 v[114:117], v[152:155], v[180:183], v[114:117]
	v_mfma_f32_16x16x32_bf16 v[114:117], v[156:159], v[184:187], v[114:117]
	v_mfma_f32_16x16x32_bf16 v[98:101], v[152:155], v[188:191], v[98:101]
	v_mfma_f32_16x16x32_bf16 v[98:101], v[156:159], v[192:195], v[98:101]
	v_mfma_f32_16x16x32_bf16 v[82:85], v[152:155], v[202:205], v[82:85]
	v_mfma_f32_16x16x32_bf16 v[82:85], v[156:159], v[206:209], v[82:85]
	v_mfma_f32_16x16x32_bf16 v[66:69], v[152:155], v[210:213], v[66:69]
	v_mfma_f32_16x16x32_bf16 v[66:69], v[156:159], v[214:217], v[66:69]
	v_mfma_f32_16x16x32_bf16 v[126:129], v[160:163], v[180:183], v[126:129]
	v_mfma_f32_16x16x32_bf16 v[126:129], v[164:167], v[184:187], v[126:129]
	v_mfma_f32_16x16x32_bf16 v[110:113], v[160:163], v[188:191], v[110:113]
	v_mfma_f32_16x16x32_bf16 v[110:113], v[164:167], v[192:195], v[110:113]
	v_mfma_f32_16x16x32_bf16 v[94:97], v[160:163], v[202:205], v[94:97]
	v_mfma_f32_16x16x32_bf16 v[94:97], v[164:167], v[206:209], v[94:97]
	v_mfma_f32_16x16x32_bf16 v[78:81], v[160:163], v[210:213], v[78:81]
	v_mfma_f32_16x16x32_bf16 v[78:81], v[164:167], v[214:217], v[78:81]
	v_mfma_f32_16x16x32_bf16 v[122:125], v[168:171], v[180:183], v[122:125]
	v_mfma_f32_16x16x32_bf16 v[122:125], v[172:175], v[184:187], v[122:125]
	v_mfma_f32_16x16x32_bf16 v[106:109], v[168:171], v[188:191], v[106:109]
	v_mfma_f32_16x16x32_bf16 v[106:109], v[172:175], v[192:195], v[106:109]
	v_mfma_f32_16x16x32_bf16 v[90:93], v[168:171], v[202:205], v[90:93]
	v_mfma_f32_16x16x32_bf16 v[90:93], v[172:175], v[206:209], v[90:93]
	v_mfma_f32_16x16x32_bf16 v[74:77], v[168:171], v[210:213], v[74:77]
	v_mfma_f32_16x16x32_bf16 v[74:77], v[172:175], v[214:217], v[74:77]
	s_setprio 0
	s_barrier
; #define PG8_STAGE(bufoff, gbase, voff) do { _Pragma("unroll") for (int _i = 0; _i < 2; ++_i) \
;         __builtin_amdgcn_global_load_lds((const unsigned*)((const char*)(gbase) + (voff)[_i]), (PG8_LAS unsigned*)(lds + (bufoff) + ldsw + _i * 8192), 16, 0, 0); } while (0)
; #define PG8_LDA(dst, b, h) do { _Pragma("unroll") for (int m = 0; m < 4; ++m) _Pragma("unroll") for (int k = 0; k < 2; ++k) dst[m][k] = *(const PG8_LAS bf16x8*)(lds + PG8_SA(b, h) + aoff + m * 2048 + k * 1024); } while (0)
; #define PG8_MMA(ai, bj, At, Bt) do { __builtin_amdgcn_s_setprio(1); _Pragma("unroll") for (int m = 0; m < 4; ++m) _Pragma("unroll") for (int n = 0; n < 2; ++n) _Pragma("unroll") for (int k = 0; k < 2; ++k) \
;         acc[ai][bj][m][n] = __builtin_amdgcn_mfma_f32_16x16x32_bf16(Bt[n][k], At[m][k], acc[ai][bj][m][n], 0, 0, 0); __builtin_amdgcn_s_setprio(0); } while (0)
; #define PG8_WAIT_V(n) asm volatile("s_waitcnt vmcnt(" #n ")" ::: "memory")
; #define PG8_WAIT_L(n) asm volatile("s_waitcnt lgkmcnt(" #n ")" ::: "memory")
; #define PG8_BAR __builtin_amdgcn_s_barrier()
; #define PG8_SCHED __builtin_amdgcn_sched_barrier(0)
; template <class Epi, class Sched, bool ALIGN_EPI = false, bool SP2 = false>
; __device__ __forceinline__ void gemm_phase(PG8_LAS unsigned char* lds, const Gemm g, const Sched& S, const Epi& E) {
;     ...
;             PG8_LDA(At, 1, 1); PG8_STAGE(PG8_SB(1, 0), b3, voffB); PG8_STAGE(PG8_SB(1, 1), b3 + hstep, voffB); PG8_STAGE(PG8_SA(1, 0), a3, voffA);
;             PG8_WAIT_V(8); PG8_WAIT_L(0); PG8_BAR; PG8_MMA(1, 0, At, B0); PG8_MMA(1, 1, At, B1); PG8_BAR; PG8_SCHED;
;     ...
;         if constexpr (ALIGN_EPI) { if (wr == 0) PG8_BAR; }
	s_add_i32 s18, s18, s91
	v_lshl_add_u64 v[218:219], v[218:219], 0, s[30:31]
	s_mov_b32 m0, s18
	ds_read_b128 v[180:183], v178 offset:49152
	ds_read_b128 v[184:187], v178 offset:50176
	ds_read_b128 v[188:191], v178 offset:51200
	ds_read_b128 v[192:195], v178 offset:52224
	ds_read_b128 v[202:205], v178 offset:53248
	ds_read_b128 v[206:209], v178 offset:54272
	ds_read_b128 v[210:213], v178 offset:55296
	ds_read_b128 v[214:217], v178 offset:56320
	global_load_lds_dwordx4 v[218:219], off
	s_add_i32 m0, s18, 0x2000
	s_add_u32 s38, s44, 0x40080
	v_lshl_add_u64 v[218:219], v[220:221], 0, s[30:31]
	s_addc_u32 s39, s45, 0
	s_add_i32 s18, vcc_lo, s91
	global_load_lds_dwordx4 v[218:219], off
	v_lshl_add_u64 v[218:219], s[38:39], 0, v[134:135]
	s_mov_b32 m0, s18
	s_nop 0
	global_load_lds_dwordx4 v[218:219], off
	v_lshl_add_u64 v[218:219], s[38:39], 0, v[130:131]
	s_add_i32 m0, s18, 0x2000
	s_nop 0
	global_load_lds_dwordx4 v[218:219], off
	v_lshl_add_u64 v[218:219], v[222:223], 0, s[30:31]
	s_mov_b32 m0, s7
	s_nop 0
	global_load_lds_dwordx4 v[218:219], off
	v_lshl_add_u64 v[218:219], v[224:225], 0, s[30:31]
	s_mov_b32 m0, s96
	s_nop 0
	global_load_lds_dwordx4 v[218:219], off
	s_waitcnt vmcnt(8)
	s_waitcnt lgkmcnt(0)
	s_barrier
	s_setprio 1
	v_mfma_f32_16x16x32_bf16 v[54:57], v[144:147], v[180:183], v[54:57]
	v_mfma_f32_16x16x32_bf16 v[54:57], v[148:151], v[184:187], v[54:57]
	v_mfma_f32_16x16x32_bf16 v[38:41], v[144:147], v[188:191], v[38:41]
	v_mfma_f32_16x16x32_bf16 v[38:41], v[148:151], v[192:195], v[38:41]
	v_mfma_f32_16x16x32_bf16 v[22:25], v[144:147], v[202:205], v[22:25]
	v_mfma_f32_16x16x32_bf16 v[22:25], v[148:151], v[206:209], v[22:25]
	v_mfma_f32_16x16x32_bf16 v[6:9], v[144:147], v[210:213], v[6:9]
	v_mfma_f32_16x16x32_bf16 v[6:9], v[148:151], v[214:217], v[6:9]
	v_mfma_f32_16x16x32_bf16 v[50:53], v[152:155], v[180:183], v[50:53]
	v_mfma_f32_16x16x32_bf16 v[50:53], v[156:159], v[184:187], v[50:53]
	v_mfma_f32_16x16x32_bf16 v[34:37], v[152:155], v[188:191], v[34:37]
	v_mfma_f32_16x16x32_bf16 v[34:37], v[156:159], v[192:195], v[34:37]
	v_mfma_f32_16x16x32_bf16 v[18:21], v[152:155], v[202:205], v[18:21]
	v_mfma_f32_16x16x32_bf16 v[18:21], v[156:159], v[206:209], v[18:21]
	v_mfma_f32_16x16x32_bf16 v[2:5], v[152:155], v[210:213], v[2:5]
	v_mfma_f32_16x16x32_bf16 v[2:5], v[156:159], v[214:217], v[2:5]
	s_add_i32 s85, s85, 2
	s_add_u32 s46, s46, 0x100
	s_addc_u32 s47, s47, 0
	s_add_u32 s83, s83, 0x100
	s_addc_u32 s84, s84, 0
	s_cmp_gt_u32 s85, 13
	v_mfma_f32_16x16x32_bf16 v[62:65], v[160:163], v[180:183], v[62:65]
	v_mfma_f32_16x16x32_bf16 v[62:65], v[164:167], v[184:187], v[62:65]
	v_mfma_f32_16x16x32_bf16 v[46:49], v[160:163], v[188:191], v[46:49]
	v_mfma_f32_16x16x32_bf16 v[46:49], v[164:167], v[192:195], v[46:49]
	v_mfma_f32_16x16x32_bf16 v[30:33], v[160:163], v[202:205], v[30:33]
	v_mfma_f32_16x16x32_bf16 v[30:33], v[164:167], v[206:209], v[30:33]
	v_mfma_f32_16x16x32_bf16 v[10:13], v[160:163], v[210:213], v[10:13]
	v_mfma_f32_16x16x32_bf16 v[10:13], v[164:167], v[214:217], v[10:13]
	v_mfma_f32_16x16x32_bf16 v[58:61], v[168:171], v[180:183], v[58:61]
	v_mfma_f32_16x16x32_bf16 v[58:61], v[172:175], v[184:187], v[58:61]
	v_mfma_f32_16x16x32_bf16 v[42:45], v[168:171], v[188:191], v[42:45]
	v_mfma_f32_16x16x32_bf16 v[42:45], v[172:175], v[192:195], v[42:45]
	v_mfma_f32_16x16x32_bf16 v[26:29], v[168:171], v[202:205], v[26:29]
	v_mfma_f32_16x16x32_bf16 v[26:29], v[172:175], v[206:209], v[26:29]
	v_mfma_f32_16x16x32_bf16 v[14:17], v[168:171], v[210:213], v[14:17]
	v_mfma_f32_16x16x32_bf16 v[14:17], v[172:175], v[214:217], v[14:17]
	s_setprio 0
	s_barrier
	s_cbranch_scc0 .LBB0_132
	s_and_b64 vcc, exec, s[10:11]
	s_cbranch_vccz .LBB0_135
	s_barrier

; #define PG8_STAGE(bufoff, gbase, voff) do { _Pragma("unroll") for (int _i = 0; _i < 2; ++_i) \
;         __builtin_amdgcn_global_load_lds((const unsigned*)((const char*)(gbase) + (voff)[_i]), (PG8_LAS unsigned*)(lds + (bufoff) + ldsw + _i * 8192), 16, 0, 0); } while (0)
; #define PG8_LDA(dst, b, h) do { _Pragma("unroll") for (int m = 0; m < 4; ++m) _Pragma("unroll") for (int k = 0; k < 2; ++k) dst[m][k] = *(const PG8_LAS bf16x8*)(lds + PG8_SA(b, h) + aoff + m * 2048 + k * 1024); } while (0)
; #define PG8_LDB(dst, b, h) do { _Pragma("unroll") for (int n = 0; n < 2; ++n) _Pragma("unroll") for (int k = 0; k < 2; ++k) dst[n][k] = *(const PG8_LAS bf16x8*)(lds + PG8_SB(b, h) + boff + n * 2048 + k * 1024); } while (0)
; #define PG8_MMA(ai, bj, At, Bt) do { __builtin_amdgcn_s_setprio(1); _Pragma("unroll") for (int m = 0; m < 4; ++m) _Pragma("unroll") for (int n = 0; n < 2; ++n) _Pragma("unroll") for (int k = 0; k < 2; ++k) \
;         acc[ai][bj][m][n] = __builtin_amdgcn_mfma_f32_16x16x32_bf16(Bt[n][k], At[m][k], acc[ai][bj][m][n], 0, 0, 0); __builtin_amdgcn_s_setprio(0); } while (0)
; #define PG8_WAIT_V(n) asm volatile("s_waitcnt vmcnt(" #n ")" ::: "memory")
; #define PG8_WAIT_L(n) asm volatile("s_waitcnt lgkmcnt(" #n ")" ::: "memory")
; template <class Epi, class Sched, bool ALIGN_EPI = false, bool SP2 = false>
; __device__ __forceinline__ void gemm_phase(PG8_LAS unsigned char* lds, const Gemm g, const Sched& S, const Epi& E) {
;     ...
;             const bool last = (t == nt - 2);
;             const char* a1 = cA + (size_t)(t + 1) * kstep;
;             const char* a2 = last ? nA : cA + (size_t)(t + 2) * kstep; const char* b2 = last ? nB : cB + (size_t)(t + 2) * kstep;
;             const char* a3 = a2 + kstep; const char* b3 = b2 + kstep;
;             if (last && has_next) S.a_ready(nxt);
;             if constexpr (SP2) {
;             PG8_LDB(B0, 0, 0); PG8_LDB(B1, 0, 1); PG8_SCHED; PG8_LDA(At, 0, 0); PG8_STAGE(PG8_SA(1, 1), a1 + hstep, voffA);
;             PG8_WAIT_V(8); PG8_WAIT_L(0); PG8_BAR; PG8_MMA(0, 0, At, B0); PG8_MMA(0, 1, At, B1); PG8_BAR; PG8_SCHED;
;             PG8_LDA(At, 0, 1); PG8_STAGE(PG8_SB(0, 0), b2, voffB); PG8_STAGE(PG8_SB(0, 1), b2 + hstep, voffB); PG8_STAGE(PG8_SA(0, 0), a2, voffA);
;             PG8_WAIT_V(8); PG8_WAIT_L(0); PG8_BAR; PG8_MMA(1, 0, At, B0); PG8_MMA(1, 1, At, B1); PG8_BAR; PG8_SCHED;
.LBB0_220:
	s_add_i32 s39, 0, 0x10000
	v_add_u32_e32 v145, s39, v141
	s_add_i32 s18, 0, 0x14000
	ds_read_b128 v[146:149], v145
	ds_read_b128 v[150:153], v145 offset:1024
	ds_read_b128 v[154:157], v145 offset:2048
	ds_read_b128 v[158:161], v145 offset:3072
	v_add_u32_e32 v145, s18, v141
	ds_read_b128 v[162:165], v145
	ds_read_b128 v[166:169], v145 offset:1024
	ds_read_b128 v[170:173], v145 offset:2048
	ds_read_b128 v[174:177], v145 offset:3072
	ds_read_b128 v[178:181], v144
	ds_read_b128 v[182:185], v144 offset:1024
	ds_read_b128 v[186:189], v144 offset:2048
	ds_read_b128 v[190:193], v144 offset:3072
	ds_read_b128 v[202:205], v144 offset:4096
	ds_read_b128 v[206:209], v144 offset:5120
	ds_read_b128 v[210:213], v144 offset:6144
	ds_read_b128 v[214:217], v144 offset:7168
	s_add_u32 s100, s60, 0xfffc0080
	s_addc_u32 s101, s61, -1
	s_cmp_eq_u32 s82, 12
	s_cselect_b32 s65, s47, s101
	s_cselect_b32 s64, s78, s100
	s_cselect_b32 s57, s49, s81
	s_cselect_b32 s56, s79, s80
	s_add_i32 m0, s29, 0xc000
	v_lshl_add_u64 v[194:195], s[60:61], 0, v[136:137]
	global_load_lds_dwordx4 v[194:195], off
	v_lshl_add_u64 v[194:195], s[60:61], 0, v[138:139]
	s_add_i32 m0, s29, 0xe000
	s_nop 0
	global_load_lds_dwordx4 v[194:195], off
	s_waitcnt vmcnt(8)
	s_waitcnt lgkmcnt(0)
	s_barrier
	s_setprio 1
	v_mfma_f32_16x16x32_bf16 v[114:117], v[146:149], v[178:181], v[114:117]
	v_mfma_f32_16x16x32_bf16 v[114:117], v[150:153], v[182:185], v[114:117]
	v_mfma_f32_16x16x32_bf16 v[98:101], v[146:149], v[186:189], v[98:101]
	v_mfma_f32_16x16x32_bf16 v[98:101], v[150:153], v[190:193], v[98:101]
	v_mfma_f32_16x16x32_bf16 v[82:85], v[146:149], v[202:205], v[82:85]
	v_mfma_f32_16x16x32_bf16 v[82:85], v[150:153], v[206:209], v[82:85]
	v_mfma_f32_16x16x32_bf16 v[66:69], v[146:149], v[210:213], v[66:69]
	v_mfma_f32_16x16x32_bf16 v[66:69], v[150:153], v[214:217], v[66:69]
	v_mfma_f32_16x16x32_bf16 v[118:121], v[154:157], v[178:181], v[118:121]
	v_mfma_f32_16x16x32_bf16 v[118:121], v[158:161], v[182:185], v[118:121]
	v_mfma_f32_16x16x32_bf16 v[102:105], v[154:157], v[186:189], v[102:105]
	v_mfma_f32_16x16x32_bf16 v[102:105], v[158:161], v[190:193], v[102:105]
	v_mfma_f32_16x16x32_bf16 v[86:89], v[154:157], v[202:205], v[86:89]
	v_mfma_f32_16x16x32_bf16 v[86:89], v[158:161], v[206:209], v[86:89]
	v_mfma_f32_16x16x32_bf16 v[70:73], v[154:157], v[210:213], v[70:73]
	v_mfma_f32_16x16x32_bf16 v[70:73], v[158:161], v[214:217], v[70:73]
	v_mfma_f32_16x16x32_bf16 v[122:125], v[162:165], v[178:181], v[122:125]
	v_mfma_f32_16x16x32_bf16 v[122:125], v[166:169], v[182:185], v[122:125]
	v_mfma_f32_16x16x32_bf16 v[106:109], v[162:165], v[186:189], v[106:109]
	v_mfma_f32_16x16x32_bf16 v[106:109], v[166:169], v[190:193], v[106:109]
	v_mfma_f32_16x16x32_bf16 v[90:93], v[162:165], v[202:205], v[90:93]
	v_mfma_f32_16x16x32_bf16 v[90:93], v[166:169], v[206:209], v[90:93]
	v_mfma_f32_16x16x32_bf16 v[74:77], v[162:165], v[210:213], v[74:77]
	v_mfma_f32_16x16x32_bf16 v[74:77], v[166:169], v[214:217], v[74:77]
	v_mfma_f32_16x16x32_bf16 v[126:129], v[170:173], v[178:181], v[126:129]
	v_mfma_f32_16x16x32_bf16 v[126:129], v[174:177], v[182:185], v[126:129]
	v_mfma_f32_16x16x32_bf16 v[110:113], v[170:173], v[186:189], v[110:113]
	v_mfma_f32_16x16x32_bf16 v[110:113], v[174:177], v[190:193], v[110:113]
	v_mfma_f32_16x16x32_bf16 v[94:97], v[170:173], v[202:205], v[94:97]
	v_mfma_f32_16x16x32_bf16 v[94:97], v[174:177], v[206:209], v[94:97]
	v_mfma_f32_16x16x32_bf16 v[78:81], v[170:173], v[210:213], v[78:81]
	v_mfma_f32_16x16x32_bf16 v[78:81], v[174:177], v[214:217], v[78:81]
	s_setprio 0
	s_barrier
	s_add_i32 s38, s39, s27
	v_lshl_add_u64 v[194:195], s[56:57], 0, v[0:1]
	s_mov_b32 m0, s38
	ds_read_b128 v[178:181], v144 offset:16384
	ds_read_b128 v[182:185], v144 offset:17408
	ds_read_b128 v[186:189], v144 offset:18432
	ds_read_b128 v[190:193], v144 offset:19456
	ds_read_b128 v[202:205], v144 offset:20480
	ds_read_b128 v[206:209], v144 offset:21504
	ds_read_b128 v[210:213], v144 offset:22528
	ds_read_b128 v[214:217], v144 offset:23552
	global_load_lds_dwordx4 v[194:195], off
	s_add_i32 m0, s38, 0x2000
	s_add_u32 s38, s56, 0x40000
	v_lshl_add_u64 v[218:219], s[56:57], 0, v[130:131]
	s_addc_u32 s39, s57, 0
	s_add_i32 s18, s18, s27
	global_load_lds_dwordx4 v[218:219], off
	v_lshl_add_u64 v[220:221], s[38:39], 0, v[0:1]
	s_mov_b32 m0, s18
	v_lshl_add_u64 v[222:223], s[64:65], 0, v[132:133]
	global_load_lds_dwordx4 v[220:221], off
	v_lshl_add_u64 v[220:221], s[38:39], 0, v[130:131]
	s_add_i32 m0, s18, 0x2000
	s_nop 0
	global_load_lds_dwordx4 v[220:221], off
	v_lshl_add_u64 v[220:221], s[64:65], 0, v[134:135]
	s_mov_b32 m0, s29
	s_nop 0
	global_load_lds_dwordx4 v[220:221], off
	s_mov_b32 m0, s33
	s_nop 0
	global_load_lds_dwordx4 v[222:223], off
	s_waitcnt vmcnt(8)
	s_waitcnt lgkmcnt(0)
	s_barrier
; #define PG8_STAGE(bufoff, gbase, voff) do { _Pragma("unroll") for (int _i = 0; _i < 2; ++_i) \
;         __builtin_amdgcn_global_load_lds((const unsigned*)((const char*)(gbase) + (voff)[_i]), (PG8_LAS unsigned*)(lds + (bufoff) + ldsw + _i * 8192), 16, 0, 0); } while (0)
; #define PG8_LDA(dst, b, h) do { _Pragma("unroll") for (int m = 0; m < 4; ++m) _Pragma("unroll") for (int k = 0; k < 2; ++k) dst[m][k] = *(const PG8_LAS bf16x8*)(lds + PG8_SA(b, h) + aoff + m * 2048 + k * 1024); } while (0)
; #define PG8_LDB(dst, b, h) do { _Pragma("unroll") for (int n = 0; n < 2; ++n) _Pragma("unroll") for (int k = 0; k < 2; ++k) dst[n][k] = *(const PG8_LAS bf16x8*)(lds + PG8_SB(b, h) + boff + n * 2048 + k * 1024); } while (0)
; #define PG8_MMA(ai, bj, At, Bt) do { __builtin_amdgcn_s_setprio(1); _Pragma("unroll") for (int m = 0; m < 4; ++m) _Pragma("unroll") for (int n = 0; n < 2; ++n) _Pragma("unroll") for (int k = 0; k < 2; ++k) \
;         acc[ai][bj][m][n] = __builtin_amdgcn_mfma_f32_16x16x32_bf16(Bt[n][k], At[m][k], acc[ai][bj][m][n], 0, 0, 0); __builtin_amdgcn_s_setprio(0); } while (0)
; #define PG8_WAIT_V(n) asm volatile("s_waitcnt vmcnt(" #n ")" ::: "memory")
; #define PG8_WAIT_L(n) asm volatile("s_waitcnt lgkmcnt(" #n ")" ::: "memory")
; #define PG8_BAR __builtin_amdgcn_s_barrier()
; #define PG8_SCHED __builtin_amdgcn_sched_barrier(0)
; template <class Epi, class Sched, bool ALIGN_EPI = false, bool SP2 = false>
; __device__ __forceinline__ void gemm_phase(PG8_LAS unsigned char* lds, const Gemm g, const Sched& S, const Epi& E) {
;     ...
;             PG8_WAIT_V(8); PG8_WAIT_L(0); PG8_BAR; PG8_MMA(1, 0, At, B0); PG8_MMA(1, 1, At, B1); PG8_BAR; PG8_SCHED;
;             PG8_LDB(B0, 1, 0); PG8_LDB(B1, 1, 1); PG8_SCHED; PG8_LDA(At, 1, 0); PG8_STAGE(PG8_SA(0, 1), a2 + hstep, voffA);
;             PG8_WAIT_V(8); PG8_WAIT_L(0); PG8_BAR; PG8_MMA(0, 0, At, B0); PG8_MMA(0, 1, At, B1); PG8_BAR; PG8_SCHED;
	s_setprio 1
	v_mfma_f32_16x16x32_bf16 v[50:53], v[146:149], v[178:181], v[50:53]
	v_mfma_f32_16x16x32_bf16 v[50:53], v[150:153], v[182:185], v[50:53]
	v_mfma_f32_16x16x32_bf16 v[34:37], v[146:149], v[186:189], v[34:37]
	v_mfma_f32_16x16x32_bf16 v[34:37], v[150:153], v[190:193], v[34:37]
	v_mfma_f32_16x16x32_bf16 v[18:21], v[146:149], v[202:205], v[18:21]
	v_mfma_f32_16x16x32_bf16 v[18:21], v[150:153], v[206:209], v[18:21]
	v_mfma_f32_16x16x32_bf16 v[2:5], v[146:149], v[210:213], v[2:5]
	v_mfma_f32_16x16x32_bf16 v[2:5], v[150:153], v[214:217], v[2:5]
	v_mfma_f32_16x16x32_bf16 v[54:57], v[154:157], v[178:181], v[54:57]
	v_mfma_f32_16x16x32_bf16 v[54:57], v[158:161], v[182:185], v[54:57]
	v_mfma_f32_16x16x32_bf16 v[38:41], v[154:157], v[186:189], v[38:41]
	v_mfma_f32_16x16x32_bf16 v[38:41], v[158:161], v[190:193], v[38:41]
	v_mfma_f32_16x16x32_bf16 v[22:25], v[154:157], v[202:205], v[22:25]
	v_mfma_f32_16x16x32_bf16 v[22:25], v[158:161], v[206:209], v[22:25]
	v_mfma_f32_16x16x32_bf16 v[6:9], v[154:157], v[210:213], v[6:9]
	v_mfma_f32_16x16x32_bf16 v[6:9], v[158:161], v[214:217], v[6:9]
	v_mfma_f32_16x16x32_bf16 v[58:61], v[162:165], v[178:181], v[58:61]
	v_mfma_f32_16x16x32_bf16 v[58:61], v[166:169], v[182:185], v[58:61]
	v_mfma_f32_16x16x32_bf16 v[42:45], v[162:165], v[186:189], v[42:45]
	v_mfma_f32_16x16x32_bf16 v[42:45], v[166:169], v[190:193], v[42:45]
	v_mfma_f32_16x16x32_bf16 v[26:29], v[162:165], v[202:205], v[26:29]
	v_mfma_f32_16x16x32_bf16 v[26:29], v[166:169], v[206:209], v[26:29]
	v_mfma_f32_16x16x32_bf16 v[10:13], v[162:165], v[210:213], v[10:13]
	v_mfma_f32_16x16x32_bf16 v[10:13], v[166:169], v[214:217], v[10:13]
	v_mfma_f32_16x16x32_bf16 v[62:65], v[170:173], v[178:181], v[62:65]
	v_mfma_f32_16x16x32_bf16 v[62:65], v[174:177], v[182:185], v[62:65]
	v_mfma_f32_16x16x32_bf16 v[46:49], v[170:173], v[186:189], v[46:49]
	v_mfma_f32_16x16x32_bf16 v[46:49], v[174:177], v[190:193], v[46:49]
	v_mfma_f32_16x16x32_bf16 v[30:33], v[170:173], v[202:205], v[30:33]
	v_mfma_f32_16x16x32_bf16 v[30:33], v[174:177], v[206:209], v[30:33]
	v_mfma_f32_16x16x32_bf16 v[14:17], v[170:173], v[210:213], v[14:17]
	v_mfma_f32_16x16x32_bf16 v[14:17], v[174:177], v[214:217], v[14:17]
	s_setprio 0
	s_barrier
	s_add_i32 s18, 0, 0x18000
	v_add_u32_e32 v145, s18, v141
	s_add_i32 s83, 0, 0x1c000
	ds_read_b128 v[146:149], v145
	ds_read_b128 v[150:153], v145 offset:1024
	ds_read_b128 v[154:157], v145 offset:2048
	ds_read_b128 v[158:161], v145 offset:3072
	v_add_u32_e32 v145, s83, v141
	ds_read_b128 v[162:165], v145
	ds_read_b128 v[166:169], v145 offset:1024
	ds_read_b128 v[170:173], v145 offset:2048
	ds_read_b128 v[174:177], v145 offset:3072
	s_add_u32 s38, s64, 0x40000
	s_addc_u32 s39, s65, 0
	s_mov_b32 m0, s58
	v_lshl_add_u64 v[224:225], s[38:39], 0, v[134:135]
	ds_read_b128 v[178:181], v144 offset:32768
	ds_read_b128 v[182:185], v144 offset:33792
	ds_read_b128 v[186:189], v144 offset:34816
	ds_read_b128 v[190:193], v144 offset:35840
	ds_read_b128 v[202:205], v144 offset:36864
	ds_read_b128 v[206:209], v144 offset:37888
	ds_read_b128 v[210:213], v144 offset:38912
	ds_read_b128 v[214:217], v144 offset:39936
	global_load_lds_dwordx4 v[224:225], off
	v_lshl_add_u64 v[224:225], s[38:39], 0, v[132:133]
	s_mov_b32 m0, s69
	s_nop 0
	global_load_lds_dwordx4 v[224:225], off
	s_waitcnt vmcnt(8)
	s_waitcnt lgkmcnt(0)
	s_barrier
	s_setprio 1
	v_mfma_f32_16x16x32_bf16 v[114:117], v[146:149], v[178:181], v[114:117]
	v_mfma_f32_16x16x32_bf16 v[114:117], v[150:153], v[182:185], v[114:117]
	v_mfma_f32_16x16x32_bf16 v[98:101], v[146:149], v[186:189], v[98:101]
	v_mfma_f32_16x16x32_bf16 v[98:101], v[150:153], v[190:193], v[98:101]
	v_mfma_f32_16x16x32_bf16 v[82:85], v[146:149], v[202:205], v[82:85]
	v_mfma_f32_16x16x32_bf16 v[82:85], v[150:153], v[206:209], v[82:85]
	v_mfma_f32_16x16x32_bf16 v[66:69], v[146:149], v[210:213], v[66:69]
	v_mfma_f32_16x16x32_bf16 v[66:69], v[150:153], v[214:217], v[66:69]
	v_mfma_f32_16x16x32_bf16 v[118:121], v[154:157], v[178:181], v[118:121]
	v_mfma_f32_16x16x32_bf16 v[118:121], v[158:161], v[182:185], v[118:121]
	v_mfma_f32_16x16x32_bf16 v[102:105], v[154:157], v[186:189], v[102:105]
	v_mfma_f32_16x16x32_bf16 v[102:105], v[158:161], v[190:193], v[102:105]
	v_mfma_f32_16x16x32_bf16 v[86:89], v[154:157], v[202:205], v[86:89]
	v_mfma_f32_16x16x32_bf16 v[86:89], v[158:161], v[206:209], v[86:89]
	v_mfma_f32_16x16x32_bf16 v[70:73], v[154:157], v[210:213], v[70:73]
	v_mfma_f32_16x16x32_bf16 v[70:73], v[158:161], v[214:217], v[70:73]
	v_mfma_f32_16x16x32_bf16 v[122:125], v[162:165], v[178:181], v[122:125]
	v_mfma_f32_16x16x32_bf16 v[122:125], v[166:169], v[182:185], v[122:125]
	v_mfma_f32_16x16x32_bf16 v[106:109], v[162:165], v[186:189], v[106:109]
	v_mfma_f32_16x16x32_bf16 v[106:109], v[166:169], v[190:193], v[106:109]
	v_mfma_f32_16x16x32_bf16 v[90:93], v[162:165], v[202:205], v[90:93]
	v_mfma_f32_16x16x32_bf16 v[90:93], v[166:169], v[206:209], v[90:93]
	v_mfma_f32_16x16x32_bf16 v[74:77], v[162:165], v[210:213], v[74:77]
	v_mfma_f32_16x16x32_bf16 v[74:77], v[166:169], v[214:217], v[74:77]
	v_mfma_f32_16x16x32_bf16 v[126:129], v[170:173], v[178:181], v[126:129]
	v_mfma_f32_16x16x32_bf16 v[126:129], v[174:177], v[182:185], v[126:129]
	v_mfma_f32_16x16x32_bf16 v[110:113], v[170:173], v[186:189], v[110:113]
	v_mfma_f32_16x16x32_bf16 v[110:113], v[174:177], v[190:193], v[110:113]
	v_mfma_f32_16x16x32_bf16 v[94:97], v[170:173], v[202:205], v[94:97]
	v_mfma_f32_16x16x32_bf16 v[94:97], v[174:177], v[206:209], v[94:97]
	v_mfma_f32_16x16x32_bf16 v[78:81], v[170:173], v[210:213], v[78:81]
	v_mfma_f32_16x16x32_bf16 v[78:81], v[174:177], v[214:217], v[78:81]
	s_setprio 0
	s_barrier
; #define PG8_STAGE(bufoff, gbase, voff) do { _Pragma("unroll") for (int _i = 0; _i < 2; ++_i) \
;         __builtin_amdgcn_global_load_lds((const unsigned*)((const char*)(gbase) + (voff)[_i]), (PG8_LAS unsigned*)(lds + (bufoff) + ldsw + _i * 8192), 16, 0, 0); } while (0)
; #define PG8_LDA(dst, b, h) do { _Pragma("unroll") for (int m = 0; m < 4; ++m) _Pragma("unroll") for (int k = 0; k < 2; ++k) dst[m][k] = *(const PG8_LAS bf16x8*)(lds + PG8_SA(b, h) + aoff + m * 2048 + k * 1024); } while (0)
; #define PG8_MMA(ai, bj, At, Bt) do { __builtin_amdgcn_s_setprio(1); _Pragma("unroll") for (int m = 0; m < 4; ++m) _Pragma("unroll") for (int n = 0; n < 2; ++n) _Pragma("unroll") for (int k = 0; k < 2; ++k) \
;         acc[ai][bj][m][n] = __builtin_amdgcn_mfma_f32_16x16x32_bf16(Bt[n][k], At[m][k], acc[ai][bj][m][n], 0, 0, 0); __builtin_amdgcn_s_setprio(0); } while (0)
; #define PG8_WAIT_V(n) asm volatile("s_waitcnt vmcnt(" #n ")" ::: "memory")
; #define PG8_WAIT_L(n) asm volatile("s_waitcnt lgkmcnt(" #n ")" ::: "memory")
; #define PG8_BAR __builtin_amdgcn_s_barrier()
; #define PG8_SCHED __builtin_amdgcn_sched_barrier(0)
; template <class Epi, class Sched, bool ALIGN_EPI = false, bool SP2 = false>
; __device__ __forceinline__ void gemm_phase(PG8_LAS unsigned char* lds, const Gemm g, const Sched& S, const Epi& E) {
;     ...
;             PG8_LDA(At, 1, 1); PG8_STAGE(PG8_SB(1, 0), b3, voffB); PG8_STAGE(PG8_SB(1, 1), b3 + hstep, voffB); PG8_STAGE(PG8_SA(1, 0), a3, voffA);
;             PG8_WAIT_V(8); PG8_WAIT_L(0); PG8_BAR; PG8_MMA(1, 0, At, B0); PG8_MMA(1, 1, At, B1); PG8_BAR; PG8_SCHED;
;     ...
;         if constexpr (ALIGN_EPI) { if (wr == 0) PG8_BAR; }
	s_add_i32 s18, s18, s27
	v_lshl_add_u64 v[194:195], v[194:195], 0, s[30:31]
	s_mov_b32 m0, s18
	ds_read_b128 v[178:181], v144 offset:49152
	ds_read_b128 v[182:185], v144 offset:50176
	ds_read_b128 v[186:189], v144 offset:51200
	ds_read_b128 v[190:193], v144 offset:52224
	ds_read_b128 v[202:205], v144 offset:53248
	ds_read_b128 v[206:209], v144 offset:54272
	ds_read_b128 v[210:213], v144 offset:55296
	ds_read_b128 v[214:217], v144 offset:56320
	global_load_lds_dwordx4 v[194:195], off
	s_add_i32 m0, s18, 0x2000
	s_add_u32 s38, s56, 0x40080
	v_lshl_add_u64 v[194:195], v[218:219], 0, s[30:31]
	s_addc_u32 s39, s57, 0
	s_add_i32 s18, s83, s27
	global_load_lds_dwordx4 v[194:195], off
	v_lshl_add_u64 v[194:195], s[38:39], 0, v[0:1]
	s_mov_b32 m0, s18
	s_nop 0
	global_load_lds_dwordx4 v[194:195], off
	v_lshl_add_u64 v[194:195], s[38:39], 0, v[130:131]
	s_add_i32 m0, s18, 0x2000
	s_nop 0
	global_load_lds_dwordx4 v[194:195], off
	v_lshl_add_u64 v[194:195], v[220:221], 0, s[30:31]
	s_mov_b32 m0, s71
	s_nop 0
	global_load_lds_dwordx4 v[194:195], off
	v_lshl_add_u64 v[194:195], v[222:223], 0, s[30:31]
	s_mov_b32 m0, s72
	s_nop 0
	global_load_lds_dwordx4 v[194:195], off
	s_waitcnt vmcnt(8)
	s_waitcnt lgkmcnt(0)
	s_barrier
	s_setprio 1
	v_mfma_f32_16x16x32_bf16 v[50:53], v[146:149], v[178:181], v[50:53]
	v_mfma_f32_16x16x32_bf16 v[50:53], v[150:153], v[182:185], v[50:53]
	v_mfma_f32_16x16x32_bf16 v[34:37], v[146:149], v[186:189], v[34:37]
	v_mfma_f32_16x16x32_bf16 v[34:37], v[150:153], v[190:193], v[34:37]
	v_mfma_f32_16x16x32_bf16 v[18:21], v[146:149], v[202:205], v[18:21]
	v_mfma_f32_16x16x32_bf16 v[18:21], v[150:153], v[206:209], v[18:21]
	v_mfma_f32_16x16x32_bf16 v[2:5], v[146:149], v[210:213], v[2:5]
	v_mfma_f32_16x16x32_bf16 v[2:5], v[150:153], v[214:217], v[2:5]
	v_mfma_f32_16x16x32_bf16 v[54:57], v[154:157], v[178:181], v[54:57]
	v_mfma_f32_16x16x32_bf16 v[54:57], v[158:161], v[182:185], v[54:57]
	v_mfma_f32_16x16x32_bf16 v[38:41], v[154:157], v[186:189], v[38:41]
	v_mfma_f32_16x16x32_bf16 v[38:41], v[158:161], v[190:193], v[38:41]
	v_mfma_f32_16x16x32_bf16 v[22:25], v[154:157], v[202:205], v[22:25]
	v_mfma_f32_16x16x32_bf16 v[22:25], v[158:161], v[206:209], v[22:25]
	v_mfma_f32_16x16x32_bf16 v[6:9], v[154:157], v[210:213], v[6:9]
	v_mfma_f32_16x16x32_bf16 v[6:9], v[158:161], v[214:217], v[6:9]
	s_add_i32 s82, s82, 2
	s_add_u32 s60, s60, 0x100
	s_addc_u32 s61, s61, 0
	s_add_u32 s80, s80, 0x100
	s_addc_u32 s81, s81, 0
	s_cmp_gt_u32 s82, 13
	v_mfma_f32_16x16x32_bf16 v[58:61], v[162:165], v[178:181], v[58:61]
	v_mfma_f32_16x16x32_bf16 v[58:61], v[166:169], v[182:185], v[58:61]
	v_mfma_f32_16x16x32_bf16 v[42:45], v[162:165], v[186:189], v[42:45]
	v_mfma_f32_16x16x32_bf16 v[42:45], v[166:169], v[190:193], v[42:45]
	v_mfma_f32_16x16x32_bf16 v[26:29], v[162:165], v[202:205], v[26:29]
	v_mfma_f32_16x16x32_bf16 v[26:29], v[166:169], v[206:209], v[26:29]
	v_mfma_f32_16x16x32_bf16 v[10:13], v[162:165], v[210:213], v[10:13]
	v_mfma_f32_16x16x32_bf16 v[10:13], v[166:169], v[214:217], v[10:13]
	v_mfma_f32_16x16x32_bf16 v[62:65], v[170:173], v[178:181], v[62:65]
	v_mfma_f32_16x16x32_bf16 v[62:65], v[174:177], v[182:185], v[62:65]
	v_mfma_f32_16x16x32_bf16 v[46:49], v[170:173], v[186:189], v[46:49]
	v_mfma_f32_16x16x32_bf16 v[46:49], v[174:177], v[190:193], v[46:49]
	v_mfma_f32_16x16x32_bf16 v[30:33], v[170:173], v[202:205], v[30:33]
	v_mfma_f32_16x16x32_bf16 v[30:33], v[174:177], v[206:209], v[30:33]
	v_mfma_f32_16x16x32_bf16 v[14:17], v[170:173], v[210:213], v[14:17]
	v_mfma_f32_16x16x32_bf16 v[14:17], v[174:177], v[214:217], v[14:17]
	s_setprio 0
	s_barrier
	s_cbranch_scc0 .LBB0_220
	s_and_b64 vcc, exec, s[44:45]
	s_cbranch_vccz .LBB0_223
	s_barrier

; #define PG8_STAGE(bufoff, gbase, voff) do { _Pragma("unroll") for (int _i = 0; _i < 2; ++_i) \
;         __builtin_amdgcn_global_load_lds((const unsigned*)((const char*)(gbase) + (voff)[_i]), (PG8_LAS unsigned*)(lds + (bufoff) + ldsw + _i * 8192), 16, 0, 0); } while (0)
; #define PG8_LDA(dst, b, h) do { _Pragma("unroll") for (int m = 0; m < 4; ++m) _Pragma("unroll") for (int k = 0; k < 2; ++k) dst[m][k] = *(const PG8_LAS bf16x8*)(lds + PG8_SA(b, h) + aoff + m * 2048 + k * 1024); } while (0)
; #define PG8_LDB(dst, b, h) do { _Pragma("unroll") for (int n = 0; n < 2; ++n) _Pragma("unroll") for (int k = 0; k < 2; ++k) dst[n][k] = *(const PG8_LAS bf16x8*)(lds + PG8_SB(b, h) + boff + n * 2048 + k * 1024); } while (0)
; #define PG8_MMA(ai, bj, At, Bt) do { __builtin_amdgcn_s_setprio(1); _Pragma("unroll") for (int m = 0; m < 4; ++m) _Pragma("unroll") for (int n = 0; n < 2; ++n) _Pragma("unroll") for (int k = 0; k < 2; ++k) \
;         acc[ai][bj][m][n] = __builtin_amdgcn_mfma_f32_16x16x32_bf16(Bt[n][k], At[m][k], acc[ai][bj][m][n], 0, 0, 0); __builtin_amdgcn_s_setprio(0); } while (0)
; #define PG8_WAIT_V(n) asm volatile("s_waitcnt vmcnt(" #n ")" ::: "memory")
; #define PG8_WAIT_L(n) asm volatile("s_waitcnt lgkmcnt(" #n ")" ::: "memory")
; template <class Epi, class Sched, bool ALIGN_EPI = false, bool SP2 = false>
; __device__ __forceinline__ void gemm_phase(PG8_LAS unsigned char* lds, const Gemm g, const Sched& S, const Epi& E) {
;     ...
;             const bool last = (t == nt - 2);
;             const char* a1 = cA + (size_t)(t + 1) * kstep;
;             const char* a2 = last ? nA : cA + (size_t)(t + 2) * kstep; const char* b2 = last ? nB : cB + (size_t)(t + 2) * kstep;
;             const char* a3 = a2 + kstep; const char* b3 = b2 + kstep;
;             if (last && has_next) S.a_ready(nxt);
;             if constexpr (SP2) {
;             PG8_LDB(B0, 0, 0); PG8_LDB(B1, 0, 1); PG8_SCHED; PG8_LDA(At, 0, 0); PG8_STAGE(PG8_SA(1, 1), a1 + hstep, voffA);
;             PG8_WAIT_V(8); PG8_WAIT_L(0); PG8_BAR; PG8_MMA(0, 0, At, B0); PG8_MMA(0, 1, At, B1); PG8_BAR; PG8_SCHED;
;             PG8_LDA(At, 0, 1); PG8_STAGE(PG8_SB(0, 0), b2, voffB); PG8_STAGE(PG8_SB(0, 1), b2 + hstep, voffB); PG8_STAGE(PG8_SA(0, 0), a2, voffA);
;             PG8_WAIT_V(8); PG8_WAIT_L(0); PG8_BAR; PG8_MMA(1, 0, At, B0); PG8_MMA(1, 1, At, B1); PG8_BAR; PG8_SCHED;
.LBB0_274:
	s_add_i32 vcc_hi, 0, 0x10000
	s_add_i32 s18, 0, 0x14000
	v_add_u32_e32 v142, vcc_hi, v245
	v_add_u32_e32 v158, s18, v245
	ds_read_b128 v[110:113], v142
	ds_read_b128 v[118:121], v142 offset:1024
	ds_read_b128 v[138:141], v142 offset:2048
	ds_read_b128 v[142:145], v142 offset:3072
	ds_read_b128 v[146:149], v158
	ds_read_b128 v[150:153], v158 offset:1024
	ds_read_b128 v[154:157], v158 offset:2048
	ds_read_b128 v[158:161], v158 offset:3072
	ds_read_b128 v[162:165], v247
	ds_read_b128 v[166:169], v247 offset:1024
	ds_read_b128 v[170:173], v247 offset:2048
	ds_read_b128 v[174:177], v247 offset:3072
	ds_read_b128 v[178:181], v247 offset:4096
	ds_read_b128 v[182:185], v247 offset:5120
	ds_read_b128 v[186:189], v247 offset:6144
	ds_read_b128 v[190:193], v247 offset:7168
	s_add_i32 vcc_lo, s46, 2
	s_add_u32 s38, s48, 0x80
	s_addc_u32 s39, s49, 0
	s_cmp_eq_u32 s99, s46
	s_cselect_b32 s47, s81, s39
	s_cselect_b32 s46, s80, s38
	s_cselect_b32 s39, s83, s51
	s_cselect_b32 s38, s82, s50
	s_add_i32 m0, s92, 0xc000
	v_lshl_add_u64 v[210:211], s[48:49], 0, v[206:207]
	global_load_lds_dwordx4 v[210:211], off
	v_lshl_add_u64 v[210:211], s[48:49], 0, v[208:209]
	s_add_i32 m0, s92, 0xe000
	s_nop 0
	global_load_lds_dwordx4 v[210:211], off
	s_waitcnt vmcnt(8)
	s_waitcnt lgkmcnt(0)
	s_barrier
	s_setprio 1
	v_mfma_f32_16x16x32_bf16 v[130:133], v[110:113], v[162:165], v[130:133]
	v_mfma_f32_16x16x32_bf16 v[130:133], v[118:121], v[166:169], v[130:133]
	v_mfma_f32_16x16x32_bf16 v[114:117], v[110:113], v[170:173], v[114:117]
	v_mfma_f32_16x16x32_bf16 v[114:117], v[118:121], v[174:177], v[114:117]
	v_mfma_f32_16x16x32_bf16 v[94:97], v[110:113], v[178:181], v[94:97]
	v_mfma_f32_16x16x32_bf16 v[94:97], v[118:121], v[182:185], v[94:97]
	v_mfma_f32_16x16x32_bf16 v[78:81], v[110:113], v[186:189], v[78:81]
	v_mfma_f32_16x16x32_bf16 v[78:81], v[118:121], v[190:193], v[78:81]
	v_mfma_f32_16x16x32_bf16 v[134:137], v[138:141], v[162:165], v[134:137]
	v_mfma_f32_16x16x32_bf16 v[134:137], v[142:145], v[166:169], v[134:137]
	v_mfma_f32_16x16x32_bf16 v[106:109], v[138:141], v[170:173], v[106:109]
	v_mfma_f32_16x16x32_bf16 v[106:109], v[142:145], v[174:177], v[106:109]
	v_mfma_f32_16x16x32_bf16 v[90:93], v[138:141], v[178:181], v[90:93]
	v_mfma_f32_16x16x32_bf16 v[90:93], v[142:145], v[182:185], v[90:93]
	v_mfma_f32_16x16x32_bf16 v[74:77], v[138:141], v[186:189], v[74:77]
	v_mfma_f32_16x16x32_bf16 v[74:77], v[142:145], v[190:193], v[74:77]
	v_mfma_f32_16x16x32_bf16 v[126:129], v[146:149], v[162:165], v[126:129]
	v_mfma_f32_16x16x32_bf16 v[126:129], v[150:153], v[166:169], v[126:129]
	v_mfma_f32_16x16x32_bf16 v[102:105], v[146:149], v[170:173], v[102:105]
	v_mfma_f32_16x16x32_bf16 v[102:105], v[150:153], v[174:177], v[102:105]
	v_mfma_f32_16x16x32_bf16 v[86:89], v[146:149], v[178:181], v[86:89]
	v_mfma_f32_16x16x32_bf16 v[86:89], v[150:153], v[182:185], v[86:89]
	v_mfma_f32_16x16x32_bf16 v[70:73], v[146:149], v[186:189], v[70:73]
	v_mfma_f32_16x16x32_bf16 v[70:73], v[150:153], v[190:193], v[70:73]
	v_mfma_f32_16x16x32_bf16 v[122:125], v[154:157], v[162:165], v[122:125]
	v_mfma_f32_16x16x32_bf16 v[122:125], v[158:161], v[166:169], v[122:125]
	v_mfma_f32_16x16x32_bf16 v[98:101], v[154:157], v[170:173], v[98:101]
	v_mfma_f32_16x16x32_bf16 v[98:101], v[158:161], v[174:177], v[98:101]
	v_mfma_f32_16x16x32_bf16 v[82:85], v[154:157], v[178:181], v[82:85]
	v_mfma_f32_16x16x32_bf16 v[82:85], v[158:161], v[182:185], v[82:85]
	v_mfma_f32_16x16x32_bf16 v[66:69], v[154:157], v[186:189], v[66:69]
	v_mfma_f32_16x16x32_bf16 v[66:69], v[158:161], v[190:193], v[66:69]
	s_setprio 0
	s_barrier
	s_add_i32 vcc_hi, vcc_hi, s6
	v_lshl_add_u64 v[210:211], s[38:39], 0, v[0:1]
	s_mov_b32 m0, vcc_hi
	ds_read_b128 v[162:165], v247 offset:16384
	ds_read_b128 v[166:169], v247 offset:17408
	ds_read_b128 v[170:173], v247 offset:18432
	ds_read_b128 v[174:177], v247 offset:19456
	ds_read_b128 v[178:181], v247 offset:20480
	ds_read_b128 v[182:185], v247 offset:21504
	ds_read_b128 v[186:189], v247 offset:22528
	ds_read_b128 v[190:193], v247 offset:23552
	global_load_lds_dwordx4 v[210:211], off
	s_add_i32 m0, vcc_hi, 0x2000
	v_lshl_add_u64 v[212:213], s[38:39], 0, v[204:205]
	s_add_u32 s38, s38, s58
	s_addc_u32 s39, s39, 0
	s_add_i32 s18, s18, s6
	global_load_lds_dwordx4 v[212:213], off
	v_lshl_add_u64 v[214:215], s[38:39], 0, v[0:1]
	s_mov_b32 m0, s18
	v_lshl_add_u64 v[216:217], s[38:39], 0, v[204:205]
	global_load_lds_dwordx4 v[214:215], off
	s_add_i32 m0, s18, 0x2000
	v_lshl_add_u64 v[218:219], s[46:47], 0, v[194:195]
	global_load_lds_dwordx4 v[216:217], off
	s_mov_b32 m0, s92
	v_lshl_add_u64 v[220:221], s[46:47], 0, v[202:203]
	global_load_lds_dwordx4 v[218:219], off
	s_mov_b32 m0, s93
	s_nop 0
	global_load_lds_dwordx4 v[220:221], off
	s_waitcnt vmcnt(8)
	s_waitcnt lgkmcnt(0)
	s_barrier
; #define PG8_STAGE(bufoff, gbase, voff) do { _Pragma("unroll") for (int _i = 0; _i < 2; ++_i) \
;         __builtin_amdgcn_global_load_lds((const unsigned*)((const char*)(gbase) + (voff)[_i]), (PG8_LAS unsigned*)(lds + (bufoff) + ldsw + _i * 8192), 16, 0, 0); } while (0)
; #define PG8_LDA(dst, b, h) do { _Pragma("unroll") for (int m = 0; m < 4; ++m) _Pragma("unroll") for (int k = 0; k < 2; ++k) dst[m][k] = *(const PG8_LAS bf16x8*)(lds + PG8_SA(b, h) + aoff + m * 2048 + k * 1024); } while (0)
; #define PG8_LDB(dst, b, h) do { _Pragma("unroll") for (int n = 0; n < 2; ++n) _Pragma("unroll") for (int k = 0; k < 2; ++k) dst[n][k] = *(const PG8_LAS bf16x8*)(lds + PG8_SB(b, h) + boff + n * 2048 + k * 1024); } while (0)
; #define PG8_MMA(ai, bj, At, Bt) do { __builtin_amdgcn_s_setprio(1); _Pragma("unroll") for (int m = 0; m < 4; ++m) _Pragma("unroll") for (int n = 0; n < 2; ++n) _Pragma("unroll") for (int k = 0; k < 2; ++k) \
;         acc[ai][bj][m][n] = __builtin_amdgcn_mfma_f32_16x16x32_bf16(Bt[n][k], At[m][k], acc[ai][bj][m][n], 0, 0, 0); __builtin_amdgcn_s_setprio(0); } while (0)
; #define PG8_WAIT_V(n) asm volatile("s_waitcnt vmcnt(" #n ")" ::: "memory")
; #define PG8_WAIT_L(n) asm volatile("s_waitcnt lgkmcnt(" #n ")" ::: "memory")
; #define PG8_BAR __builtin_amdgcn_s_barrier()
; #define PG8_SCHED __builtin_amdgcn_sched_barrier(0)
; template <class Epi, class Sched, bool ALIGN_EPI = false, bool SP2 = false>
; __device__ __forceinline__ void gemm_phase(PG8_LAS unsigned char* lds, const Gemm g, const Sched& S, const Epi& E) {
;     ...
;             PG8_WAIT_V(8); PG8_WAIT_L(0); PG8_BAR; PG8_MMA(1, 0, At, B0); PG8_MMA(1, 1, At, B1); PG8_BAR; PG8_SCHED;
;             PG8_LDB(B0, 1, 0); PG8_LDB(B1, 1, 1); PG8_SCHED; PG8_LDA(At, 1, 0); PG8_STAGE(PG8_SA(0, 1), a2 + hstep, voffA);
;             PG8_WAIT_V(8); PG8_WAIT_L(0); PG8_BAR; PG8_MMA(0, 0, At, B0); PG8_MMA(0, 1, At, B1); PG8_BAR; PG8_SCHED;
	s_setprio 1
	v_mfma_f32_16x16x32_bf16 v[62:65], v[110:113], v[162:165], v[62:65]
	v_mfma_f32_16x16x32_bf16 v[62:65], v[118:121], v[166:169], v[62:65]
	v_mfma_f32_16x16x32_bf16 v[46:49], v[110:113], v[170:173], v[46:49]
	v_mfma_f32_16x16x32_bf16 v[46:49], v[118:121], v[174:177], v[46:49]
	v_mfma_f32_16x16x32_bf16 v[30:33], v[110:113], v[178:181], v[30:33]
	v_mfma_f32_16x16x32_bf16 v[30:33], v[118:121], v[182:185], v[30:33]
	v_mfma_f32_16x16x32_bf16 v[14:17], v[110:113], v[186:189], v[14:17]
	v_mfma_f32_16x16x32_bf16 v[14:17], v[118:121], v[190:193], v[14:17]
	v_mfma_f32_16x16x32_bf16 v[58:61], v[138:141], v[162:165], v[58:61]
	v_mfma_f32_16x16x32_bf16 v[58:61], v[142:145], v[166:169], v[58:61]
	v_mfma_f32_16x16x32_bf16 v[42:45], v[138:141], v[170:173], v[42:45]
	v_mfma_f32_16x16x32_bf16 v[42:45], v[142:145], v[174:177], v[42:45]
	v_mfma_f32_16x16x32_bf16 v[26:29], v[138:141], v[178:181], v[26:29]
	v_mfma_f32_16x16x32_bf16 v[26:29], v[142:145], v[182:185], v[26:29]
	v_mfma_f32_16x16x32_bf16 v[10:13], v[138:141], v[186:189], v[10:13]
	v_mfma_f32_16x16x32_bf16 v[10:13], v[142:145], v[190:193], v[10:13]
	v_mfma_f32_16x16x32_bf16 v[54:57], v[146:149], v[162:165], v[54:57]
	v_mfma_f32_16x16x32_bf16 v[54:57], v[150:153], v[166:169], v[54:57]
	v_mfma_f32_16x16x32_bf16 v[38:41], v[146:149], v[170:173], v[38:41]
	v_mfma_f32_16x16x32_bf16 v[38:41], v[150:153], v[174:177], v[38:41]
	v_mfma_f32_16x16x32_bf16 v[22:25], v[146:149], v[178:181], v[22:25]
	v_mfma_f32_16x16x32_bf16 v[22:25], v[150:153], v[182:185], v[22:25]
	v_mfma_f32_16x16x32_bf16 v[6:9], v[146:149], v[186:189], v[6:9]
	v_mfma_f32_16x16x32_bf16 v[6:9], v[150:153], v[190:193], v[6:9]
	v_mfma_f32_16x16x32_bf16 v[50:53], v[154:157], v[162:165], v[50:53]
	v_mfma_f32_16x16x32_bf16 v[50:53], v[158:161], v[166:169], v[50:53]
	v_mfma_f32_16x16x32_bf16 v[34:37], v[154:157], v[170:173], v[34:37]
	v_mfma_f32_16x16x32_bf16 v[34:37], v[158:161], v[174:177], v[34:37]
	v_mfma_f32_16x16x32_bf16 v[18:21], v[154:157], v[178:181], v[18:21]
	v_mfma_f32_16x16x32_bf16 v[18:21], v[158:161], v[182:185], v[18:21]
	v_mfma_f32_16x16x32_bf16 v[2:5], v[154:157], v[186:189], v[2:5]
	v_mfma_f32_16x16x32_bf16 v[2:5], v[158:161], v[190:193], v[2:5]
	s_setprio 0
	s_barrier
	s_add_i32 s18, 0, 0x18000
	s_add_i32 vcc_hi, 0, 0x1c000
	v_add_u32_e32 v142, s18, v245
	v_add_u32_e32 v158, vcc_hi, v245
	ds_read_b128 v[110:113], v142
	ds_read_b128 v[118:121], v142 offset:1024
	ds_read_b128 v[138:141], v142 offset:2048
	ds_read_b128 v[142:145], v142 offset:3072
	ds_read_b128 v[146:149], v158
	ds_read_b128 v[150:153], v158 offset:1024
	ds_read_b128 v[154:157], v158 offset:2048
	ds_read_b128 v[158:161], v158 offset:3072
	s_add_u32 s38, s46, s58
	s_addc_u32 s39, s47, 0
	s_mov_b32 m0, s94
	v_lshl_add_u64 v[222:223], s[38:39], 0, v[194:195]
	ds_read_b128 v[162:165], v247 offset:32768
	ds_read_b128 v[166:169], v247 offset:33792
	ds_read_b128 v[170:173], v247 offset:34816
	ds_read_b128 v[174:177], v247 offset:35840
	ds_read_b128 v[178:181], v247 offset:36864
	ds_read_b128 v[182:185], v247 offset:37888
	ds_read_b128 v[186:189], v247 offset:38912
	ds_read_b128 v[190:193], v247 offset:39936
	global_load_lds_dwordx4 v[222:223], off
	v_lshl_add_u64 v[222:223], s[38:39], 0, v[202:203]
	s_mov_b32 m0, s95
	s_nop 0
	global_load_lds_dwordx4 v[222:223], off
	s_waitcnt vmcnt(8)
	s_waitcnt lgkmcnt(0)
	s_barrier
	s_setprio 1
	v_mfma_f32_16x16x32_bf16 v[130:133], v[110:113], v[162:165], v[130:133]
	v_mfma_f32_16x16x32_bf16 v[130:133], v[118:121], v[166:169], v[130:133]
	v_mfma_f32_16x16x32_bf16 v[114:117], v[110:113], v[170:173], v[114:117]
	v_mfma_f32_16x16x32_bf16 v[114:117], v[118:121], v[174:177], v[114:117]
	v_mfma_f32_16x16x32_bf16 v[94:97], v[110:113], v[178:181], v[94:97]
	v_mfma_f32_16x16x32_bf16 v[94:97], v[118:121], v[182:185], v[94:97]
	v_mfma_f32_16x16x32_bf16 v[78:81], v[110:113], v[186:189], v[78:81]
	v_mfma_f32_16x16x32_bf16 v[78:81], v[118:121], v[190:193], v[78:81]
	v_mfma_f32_16x16x32_bf16 v[134:137], v[138:141], v[162:165], v[134:137]
	v_mfma_f32_16x16x32_bf16 v[134:137], v[142:145], v[166:169], v[134:137]
	v_mfma_f32_16x16x32_bf16 v[106:109], v[138:141], v[170:173], v[106:109]
	v_mfma_f32_16x16x32_bf16 v[106:109], v[142:145], v[174:177], v[106:109]
	v_mfma_f32_16x16x32_bf16 v[90:93], v[138:141], v[178:181], v[90:93]
	v_mfma_f32_16x16x32_bf16 v[90:93], v[142:145], v[182:185], v[90:93]
	v_mfma_f32_16x16x32_bf16 v[74:77], v[138:141], v[186:189], v[74:77]
	v_mfma_f32_16x16x32_bf16 v[74:77], v[142:145], v[190:193], v[74:77]
	v_mfma_f32_16x16x32_bf16 v[126:129], v[146:149], v[162:165], v[126:129]
	v_mfma_f32_16x16x32_bf16 v[126:129], v[150:153], v[166:169], v[126:129]
	v_mfma_f32_16x16x32_bf16 v[102:105], v[146:149], v[170:173], v[102:105]
	v_mfma_f32_16x16x32_bf16 v[102:105], v[150:153], v[174:177], v[102:105]
	v_mfma_f32_16x16x32_bf16 v[86:89], v[146:149], v[178:181], v[86:89]
	v_mfma_f32_16x16x32_bf16 v[86:89], v[150:153], v[182:185], v[86:89]
	v_mfma_f32_16x16x32_bf16 v[70:73], v[146:149], v[186:189], v[70:73]
	v_mfma_f32_16x16x32_bf16 v[70:73], v[150:153], v[190:193], v[70:73]
	v_mfma_f32_16x16x32_bf16 v[122:125], v[154:157], v[162:165], v[122:125]
	v_mfma_f32_16x16x32_bf16 v[122:125], v[158:161], v[166:169], v[122:125]
	v_mfma_f32_16x16x32_bf16 v[98:101], v[154:157], v[170:173], v[98:101]
	v_mfma_f32_16x16x32_bf16 v[98:101], v[158:161], v[174:177], v[98:101]
	v_mfma_f32_16x16x32_bf16 v[82:85], v[154:157], v[178:181], v[82:85]
	v_mfma_f32_16x16x32_bf16 v[82:85], v[158:161], v[182:185], v[82:85]
	v_mfma_f32_16x16x32_bf16 v[66:69], v[154:157], v[186:189], v[66:69]
	v_mfma_f32_16x16x32_bf16 v[66:69], v[158:161], v[190:193], v[66:69]
	s_setprio 0
	s_barrier
; #define PG8_STAGE(bufoff, gbase, voff) do { _Pragma("unroll") for (int _i = 0; _i < 2; ++_i) \
;         __builtin_amdgcn_global_load_lds((const unsigned*)((const char*)(gbase) + (voff)[_i]), (PG8_LAS unsigned*)(lds + (bufoff) + ldsw + _i * 8192), 16, 0, 0); } while (0)
; #define PG8_LDA(dst, b, h) do { _Pragma("unroll") for (int m = 0; m < 4; ++m) _Pragma("unroll") for (int k = 0; k < 2; ++k) dst[m][k] = *(const PG8_LAS bf16x8*)(lds + PG8_SA(b, h) + aoff + m * 2048 + k * 1024); } while (0)
; #define PG8_MMA(ai, bj, At, Bt) do { __builtin_amdgcn_s_setprio(1); _Pragma("unroll") for (int m = 0; m < 4; ++m) _Pragma("unroll") for (int n = 0; n < 2; ++n) _Pragma("unroll") for (int k = 0; k < 2; ++k) \
;         acc[ai][bj][m][n] = __builtin_amdgcn_mfma_f32_16x16x32_bf16(Bt[n][k], At[m][k], acc[ai][bj][m][n], 0, 0, 0); __builtin_amdgcn_s_setprio(0); } while (0)
; #define PG8_WAIT_V(n) asm volatile("s_waitcnt vmcnt(" #n ")" ::: "memory")
; #define PG8_WAIT_L(n) asm volatile("s_waitcnt lgkmcnt(" #n ")" ::: "memory")
; #define PG8_BAR __builtin_amdgcn_s_barrier()
; #define PG8_SCHED __builtin_amdgcn_sched_barrier(0)
; template <class Epi, class Sched, bool ALIGN_EPI = false, bool SP2 = false>
; __device__ __forceinline__ void gemm_phase(PG8_LAS unsigned char* lds, const Gemm g, const Sched& S, const Epi& E) {
;     ...
;             PG8_LDA(At, 1, 1); PG8_STAGE(PG8_SB(1, 0), b3, voffB); PG8_STAGE(PG8_SB(1, 1), b3 + hstep, voffB); PG8_STAGE(PG8_SA(1, 0), a3, voffA);
;             PG8_WAIT_V(8); PG8_WAIT_L(0); PG8_BAR; PG8_MMA(1, 0, At, B0); PG8_MMA(1, 1, At, B1); PG8_BAR; PG8_SCHED;
;     ...
;         if constexpr (ALIGN_EPI) { if (wr == 0) PG8_BAR; }
	s_add_i32 s18, s18, s6
	v_lshl_add_u64 v[210:211], v[210:211], 0, s[30:31]
	s_mov_b32 m0, s18
	ds_read_b128 v[162:165], v247 offset:49152
	ds_read_b128 v[166:169], v247 offset:50176
	ds_read_b128 v[170:173], v247 offset:51200
	ds_read_b128 v[174:177], v247 offset:52224
	ds_read_b128 v[178:181], v247 offset:53248
	ds_read_b128 v[182:185], v247 offset:54272
	ds_read_b128 v[186:189], v247 offset:55296
	ds_read_b128 v[190:193], v247 offset:56320
	global_load_lds_dwordx4 v[210:211], off
	v_lshl_add_u64 v[210:211], v[212:213], 0, s[30:31]
	s_add_i32 m0, s18, 0x2000
	s_add_i32 s18, vcc_hi, s6
	global_load_lds_dwordx4 v[210:211], off
	v_lshl_add_u64 v[210:211], v[214:215], 0, s[30:31]
	s_mov_b32 m0, s18
	s_nop 0
	global_load_lds_dwordx4 v[210:211], off
	v_lshl_add_u64 v[210:211], v[216:217], 0, s[30:31]
	s_add_i32 m0, s18, 0x2000
	s_nop 0
	global_load_lds_dwordx4 v[210:211], off
	v_lshl_add_u64 v[210:211], v[218:219], 0, s[30:31]
	s_mov_b32 m0, s97
	s_nop 0
	global_load_lds_dwordx4 v[210:211], off
	v_lshl_add_u64 v[210:211], v[220:221], 0, s[30:31]
	s_mov_b32 m0, s98
	s_nop 0
	global_load_lds_dwordx4 v[210:211], off
	s_waitcnt vmcnt(8)
	s_waitcnt lgkmcnt(0)
	s_barrier
	s_setprio 1
	v_mfma_f32_16x16x32_bf16 v[62:65], v[110:113], v[162:165], v[62:65]
	v_mfma_f32_16x16x32_bf16 v[62:65], v[118:121], v[166:169], v[62:65]
	v_mfma_f32_16x16x32_bf16 v[46:49], v[110:113], v[170:173], v[46:49]
	v_mfma_f32_16x16x32_bf16 v[46:49], v[118:121], v[174:177], v[46:49]
	v_mfma_f32_16x16x32_bf16 v[30:33], v[110:113], v[178:181], v[30:33]
	v_mfma_f32_16x16x32_bf16 v[30:33], v[118:121], v[182:185], v[30:33]
	v_mfma_f32_16x16x32_bf16 v[14:17], v[110:113], v[186:189], v[14:17]
	v_mfma_f32_16x16x32_bf16 v[14:17], v[118:121], v[190:193], v[14:17]
	v_mfma_f32_16x16x32_bf16 v[58:61], v[138:141], v[162:165], v[58:61]
	v_mfma_f32_16x16x32_bf16 v[58:61], v[142:145], v[166:169], v[58:61]
	v_mfma_f32_16x16x32_bf16 v[42:45], v[138:141], v[170:173], v[42:45]
	v_mfma_f32_16x16x32_bf16 v[42:45], v[142:145], v[174:177], v[42:45]
	v_mfma_f32_16x16x32_bf16 v[26:29], v[138:141], v[178:181], v[26:29]
	v_mfma_f32_16x16x32_bf16 v[26:29], v[142:145], v[182:185], v[26:29]
	v_mfma_f32_16x16x32_bf16 v[10:13], v[138:141], v[186:189], v[10:13]
	v_mfma_f32_16x16x32_bf16 v[10:13], v[142:145], v[190:193], v[10:13]
	s_add_u32 s48, s48, 0x100
	s_addc_u32 s49, s49, 0
	s_add_u32 s50, s50, 0x100
	s_addc_u32 s51, s51, 0
	s_cmp_ge_u32 vcc_lo, s96
	s_mov_b32 s46, vcc_lo
	v_mfma_f32_16x16x32_bf16 v[54:57], v[146:149], v[162:165], v[54:57]
	v_mfma_f32_16x16x32_bf16 v[54:57], v[150:153], v[166:169], v[54:57]
	v_mfma_f32_16x16x32_bf16 v[38:41], v[146:149], v[170:173], v[38:41]
	v_mfma_f32_16x16x32_bf16 v[38:41], v[150:153], v[174:177], v[38:41]
	v_mfma_f32_16x16x32_bf16 v[22:25], v[146:149], v[178:181], v[22:25]
	v_mfma_f32_16x16x32_bf16 v[22:25], v[150:153], v[182:185], v[22:25]
	v_mfma_f32_16x16x32_bf16 v[6:9], v[146:149], v[186:189], v[6:9]
	v_mfma_f32_16x16x32_bf16 v[6:9], v[150:153], v[190:193], v[6:9]
	v_mfma_f32_16x16x32_bf16 v[50:53], v[154:157], v[162:165], v[50:53]
	v_mfma_f32_16x16x32_bf16 v[50:53], v[158:161], v[166:169], v[50:53]
	v_mfma_f32_16x16x32_bf16 v[34:37], v[154:157], v[170:173], v[34:37]
	v_mfma_f32_16x16x32_bf16 v[34:37], v[158:161], v[174:177], v[34:37]
	v_mfma_f32_16x16x32_bf16 v[18:21], v[154:157], v[178:181], v[18:21]
	v_mfma_f32_16x16x32_bf16 v[18:21], v[158:161], v[182:185], v[18:21]
	v_mfma_f32_16x16x32_bf16 v[2:5], v[154:157], v[186:189], v[2:5]
	v_mfma_f32_16x16x32_bf16 v[2:5], v[158:161], v[190:193], v[2:5]
	s_setprio 0
	s_barrier
	s_cbranch_scc0 .LBB0_274
	s_and_b64 vcc, exec, s[72:73]
	s_cbranch_vccz .LBB0_277
	s_barrier

; #define PG8_STAGE(bufoff, gbase, voff) do { _Pragma("unroll") for (int _i = 0; _i < 2; ++_i) \
;         __builtin_amdgcn_global_load_lds((const unsigned*)((const char*)(gbase) + (voff)[_i]), (PG8_LAS unsigned*)(lds + (bufoff) + ldsw + _i * 8192), 16, 0, 0); } while (0)
; #define PG8_LDA(dst, b, h) do { _Pragma("unroll") for (int m = 0; m < 4; ++m) _Pragma("unroll") for (int k = 0; k < 2; ++k) dst[m][k] = *(const PG8_LAS bf16x8*)(lds + PG8_SA(b, h) + aoff + m * 2048 + k * 1024); } while (0)
; #define PG8_LDB(dst, b, h) do { _Pragma("unroll") for (int n = 0; n < 2; ++n) _Pragma("unroll") for (int k = 0; k < 2; ++k) dst[n][k] = *(const PG8_LAS bf16x8*)(lds + PG8_SB(b, h) + boff + n * 2048 + k * 1024); } while (0)
; #define PG8_MMA(ai, bj, At, Bt) do { __builtin_amdgcn_s_setprio(1); _Pragma("unroll") for (int m = 0; m < 4; ++m) _Pragma("unroll") for (int n = 0; n < 2; ++n) _Pragma("unroll") for (int k = 0; k < 2; ++k) \
;         acc[ai][bj][m][n] = __builtin_amdgcn_mfma_f32_16x16x32_bf16(Bt[n][k], At[m][k], acc[ai][bj][m][n], 0, 0, 0); __builtin_amdgcn_s_setprio(0); } while (0)
; #define PG8_WAIT_V(n) asm volatile("s_waitcnt vmcnt(" #n ")" ::: "memory")
; #define PG8_WAIT_L(n) asm volatile("s_waitcnt lgkmcnt(" #n ")" ::: "memory")
; template <class Epi, class Sched, bool ALIGN_EPI = false, bool SP2 = false>
; __device__ __forceinline__ void gemm_phase(PG8_LAS unsigned char* lds, const Gemm g, const Sched& S, const Epi& E) {
;     ...
;             const bool last = (t == nt - 2);
;             const char* a1 = cA + (size_t)(t + 1) * kstep;
;             const char* a2 = last ? nA : cA + (size_t)(t + 2) * kstep; const char* b2 = last ? nB : cB + (size_t)(t + 2) * kstep;
;             const char* a3 = a2 + kstep; const char* b3 = b2 + kstep;
;             if (last && has_next) S.a_ready(nxt);
;             if constexpr (SP2) {
;             PG8_LDB(B0, 0, 0); PG8_LDB(B1, 0, 1); PG8_SCHED; PG8_LDA(At, 0, 0); PG8_STAGE(PG8_SA(1, 1), a1 + hstep, voffA);
;             PG8_WAIT_V(8); PG8_WAIT_L(0); PG8_BAR; PG8_MMA(0, 0, At, B0); PG8_MMA(0, 1, At, B1); PG8_BAR; PG8_SCHED;
;             PG8_LDA(At, 0, 1); PG8_STAGE(PG8_SB(0, 0), b2, voffB); PG8_STAGE(PG8_SB(0, 1), b2 + hstep, voffB); PG8_STAGE(PG8_SA(0, 0), a2, voffA);
;             PG8_WAIT_V(8); PG8_WAIT_L(0); PG8_BAR; PG8_MMA(1, 0, At, B0); PG8_MMA(1, 1, At, B1); PG8_BAR; PG8_SCHED;
.LBB0_408:
	s_add_i32 s85, 0, 0x10000
	v_add_u32_e32 v0, s85, v167
	s_add_i32 s38, 0, 0x14000
	ds_read_b128 v[142:145], v0
	ds_read_b128 v[146:149], v0 offset:1024
	ds_read_b128 v[150:153], v0 offset:2048
	ds_read_b128 v[154:157], v0 offset:3072
	v_add_u32_e32 v0, s38, v167
	ds_read_b128 v[158:161], v0
	ds_read_b128 v[162:165], v0 offset:1024
	ds_read_b128 v[172:175], v0 offset:2048
	ds_read_b128 v[176:179], v0 offset:3072
	ds_read_b128 v[180:183], v170
	ds_read_b128 v[184:187], v170 offset:1024
	ds_read_b128 v[188:191], v170 offset:2048
	ds_read_b128 v[192:195], v170 offset:3072
	ds_read_b128 v[202:205], v170 offset:4096
	ds_read_b128 v[206:209], v170 offset:5120
	ds_read_b128 v[210:213], v170 offset:6144
	ds_read_b128 v[214:217], v170 offset:7168
	s_add_u32 s100, s48, 0xfffc0080
	s_addc_u32 s101, s49, -1
	s_cmp_eq_u32 s84, 12
	s_cselect_b32 s73, s21, s101
	s_cselect_b32 s72, s27, s100
	s_cselect_b32 s47, s29, s69
	s_cselect_b32 s46, s33, s53
	s_add_i32 m0, s76, 0xc000
	v_lshl_add_u64 v[218:219], s[48:49], 0, v[138:139]
	global_load_lds_dwordx4 v[218:219], off
	v_lshl_add_u64 v[218:219], s[48:49], 0, v[140:141]
	s_add_i32 m0, s76, 0xe000
	s_nop 0
	global_load_lds_dwordx4 v[218:219], off
	s_waitcnt vmcnt(8)
	s_waitcnt lgkmcnt(0)
	s_barrier
	s_setprio 1
	v_mfma_f32_16x16x32_bf16 v[122:125], v[142:145], v[180:183], v[122:125]
	v_mfma_f32_16x16x32_bf16 v[122:125], v[146:149], v[184:187], v[122:125]
	v_mfma_f32_16x16x32_bf16 v[106:109], v[142:145], v[188:191], v[106:109]
	v_mfma_f32_16x16x32_bf16 v[106:109], v[146:149], v[192:195], v[106:109]
	v_mfma_f32_16x16x32_bf16 v[90:93], v[142:145], v[202:205], v[90:93]
	v_mfma_f32_16x16x32_bf16 v[90:93], v[146:149], v[206:209], v[90:93]
	v_mfma_f32_16x16x32_bf16 v[74:77], v[142:145], v[210:213], v[74:77]
	v_mfma_f32_16x16x32_bf16 v[74:77], v[146:149], v[214:217], v[74:77]
	v_mfma_f32_16x16x32_bf16 v[126:129], v[150:153], v[180:183], v[126:129]
	v_mfma_f32_16x16x32_bf16 v[126:129], v[154:157], v[184:187], v[126:129]
	v_mfma_f32_16x16x32_bf16 v[110:113], v[150:153], v[188:191], v[110:113]
	v_mfma_f32_16x16x32_bf16 v[110:113], v[154:157], v[192:195], v[110:113]
	v_mfma_f32_16x16x32_bf16 v[94:97], v[150:153], v[202:205], v[94:97]
	v_mfma_f32_16x16x32_bf16 v[94:97], v[154:157], v[206:209], v[94:97]
	v_mfma_f32_16x16x32_bf16 v[78:81], v[150:153], v[210:213], v[78:81]
	v_mfma_f32_16x16x32_bf16 v[78:81], v[154:157], v[214:217], v[78:81]
	v_mfma_f32_16x16x32_bf16 v[114:117], v[158:161], v[180:183], v[114:117]
	v_mfma_f32_16x16x32_bf16 v[114:117], v[162:165], v[184:187], v[114:117]
	v_mfma_f32_16x16x32_bf16 v[98:101], v[158:161], v[188:191], v[98:101]
	v_mfma_f32_16x16x32_bf16 v[98:101], v[162:165], v[192:195], v[98:101]
	v_mfma_f32_16x16x32_bf16 v[82:85], v[158:161], v[202:205], v[82:85]
	v_mfma_f32_16x16x32_bf16 v[82:85], v[162:165], v[206:209], v[82:85]
	v_mfma_f32_16x16x32_bf16 v[66:69], v[158:161], v[210:213], v[66:69]
	v_mfma_f32_16x16x32_bf16 v[66:69], v[162:165], v[214:217], v[66:69]
	v_mfma_f32_16x16x32_bf16 v[118:121], v[172:175], v[180:183], v[118:121]
	v_mfma_f32_16x16x32_bf16 v[118:121], v[176:179], v[184:187], v[118:121]
	v_mfma_f32_16x16x32_bf16 v[102:105], v[172:175], v[188:191], v[102:105]
	v_mfma_f32_16x16x32_bf16 v[102:105], v[176:179], v[192:195], v[102:105]
	v_mfma_f32_16x16x32_bf16 v[86:89], v[172:175], v[202:205], v[86:89]
	v_mfma_f32_16x16x32_bf16 v[86:89], v[176:179], v[206:209], v[86:89]
	v_mfma_f32_16x16x32_bf16 v[70:73], v[172:175], v[210:213], v[70:73]
	v_mfma_f32_16x16x32_bf16 v[70:73], v[176:179], v[214:217], v[70:73]
	s_setprio 0
	s_barrier
	s_add_i32 s39, s85, s75
	v_lshl_add_u64 v[218:219], s[46:47], 0, v[134:135]
	s_mov_b32 m0, s39
	ds_read_b128 v[180:183], v170 offset:16384
	ds_read_b128 v[184:187], v170 offset:17408
	ds_read_b128 v[188:191], v170 offset:18432
	ds_read_b128 v[192:195], v170 offset:19456
	ds_read_b128 v[202:205], v170 offset:20480
	ds_read_b128 v[206:209], v170 offset:21504
	ds_read_b128 v[210:213], v170 offset:22528
	ds_read_b128 v[214:217], v170 offset:23552
	global_load_lds_dwordx4 v[218:219], off
	s_add_i32 m0, s39, 0x2000
	s_add_u32 s92, s46, 0x40000
	v_lshl_add_u64 v[220:221], s[46:47], 0, v[130:131]
	s_addc_u32 s93, s47, 0
	s_add_i32 s38, s38, s75
	global_load_lds_dwordx4 v[220:221], off
	v_lshl_add_u64 v[222:223], s[92:93], 0, v[134:135]
	s_mov_b32 m0, s38
	v_lshl_add_u64 v[224:225], s[72:73], 0, v[132:133]
	global_load_lds_dwordx4 v[222:223], off
	v_lshl_add_u64 v[222:223], s[92:93], 0, v[130:131]
	s_add_i32 m0, s38, 0x2000
	s_nop 0
	global_load_lds_dwordx4 v[222:223], off
	v_lshl_add_u64 v[222:223], s[72:73], 0, v[136:137]
	s_mov_b32 m0, s76
	s_nop 0
	global_load_lds_dwordx4 v[222:223], off
	s_mov_b32 m0, s77
	s_nop 0
	global_load_lds_dwordx4 v[224:225], off
	s_waitcnt vmcnt(8)
	s_waitcnt lgkmcnt(0)
	s_barrier
; #define PG8_STAGE(bufoff, gbase, voff) do { _Pragma("unroll") for (int _i = 0; _i < 2; ++_i) \
;         __builtin_amdgcn_global_load_lds((const unsigned*)((const char*)(gbase) + (voff)[_i]), (PG8_LAS unsigned*)(lds + (bufoff) + ldsw + _i * 8192), 16, 0, 0); } while (0)
; #define PG8_LDA(dst, b, h) do { _Pragma("unroll") for (int m = 0; m < 4; ++m) _Pragma("unroll") for (int k = 0; k < 2; ++k) dst[m][k] = *(const PG8_LAS bf16x8*)(lds + PG8_SA(b, h) + aoff + m * 2048 + k * 1024); } while (0)
; #define PG8_LDB(dst, b, h) do { _Pragma("unroll") for (int n = 0; n < 2; ++n) _Pragma("unroll") for (int k = 0; k < 2; ++k) dst[n][k] = *(const PG8_LAS bf16x8*)(lds + PG8_SB(b, h) + boff + n * 2048 + k * 1024); } while (0)
; #define PG8_MMA(ai, bj, At, Bt) do { __builtin_amdgcn_s_setprio(1); _Pragma("unroll") for (int m = 0; m < 4; ++m) _Pragma("unroll") for (int n = 0; n < 2; ++n) _Pragma("unroll") for (int k = 0; k < 2; ++k) \
;         acc[ai][bj][m][n] = __builtin_amdgcn_mfma_f32_16x16x32_bf16(Bt[n][k], At[m][k], acc[ai][bj][m][n], 0, 0, 0); __builtin_amdgcn_s_setprio(0); } while (0)
; #define PG8_WAIT_V(n) asm volatile("s_waitcnt vmcnt(" #n ")" ::: "memory")
; #define PG8_WAIT_L(n) asm volatile("s_waitcnt lgkmcnt(" #n ")" ::: "memory")
; #define PG8_BAR __builtin_amdgcn_s_barrier()
; #define PG8_SCHED __builtin_amdgcn_sched_barrier(0)
; template <class Epi, class Sched, bool ALIGN_EPI = false, bool SP2 = false>
; __device__ __forceinline__ void gemm_phase(PG8_LAS unsigned char* lds, const Gemm g, const Sched& S, const Epi& E) {
;     ...
;             PG8_WAIT_V(8); PG8_WAIT_L(0); PG8_BAR; PG8_MMA(1, 0, At, B0); PG8_MMA(1, 1, At, B1); PG8_BAR; PG8_SCHED;
;             PG8_LDB(B0, 1, 0); PG8_LDB(B1, 1, 1); PG8_SCHED; PG8_LDA(At, 1, 0); PG8_STAGE(PG8_SA(0, 1), a2 + hstep, voffA);
;             PG8_WAIT_V(8); PG8_WAIT_L(0); PG8_BAR; PG8_MMA(0, 0, At, B0); PG8_MMA(0, 1, At, B1); PG8_BAR; PG8_SCHED;
	s_setprio 1
	v_mfma_f32_16x16x32_bf16 v[58:61], v[142:145], v[180:183], v[58:61]
	v_mfma_f32_16x16x32_bf16 v[58:61], v[146:149], v[184:187], v[58:61]
	v_mfma_f32_16x16x32_bf16 v[42:45], v[142:145], v[188:191], v[42:45]
	v_mfma_f32_16x16x32_bf16 v[42:45], v[146:149], v[192:195], v[42:45]
	v_mfma_f32_16x16x32_bf16 v[26:29], v[142:145], v[202:205], v[26:29]
	v_mfma_f32_16x16x32_bf16 v[26:29], v[146:149], v[206:209], v[26:29]
	v_mfma_f32_16x16x32_bf16 v[10:13], v[142:145], v[210:213], v[10:13]
	v_mfma_f32_16x16x32_bf16 v[10:13], v[146:149], v[214:217], v[10:13]
	v_mfma_f32_16x16x32_bf16 v[62:65], v[150:153], v[180:183], v[62:65]
	v_mfma_f32_16x16x32_bf16 v[62:65], v[154:157], v[184:187], v[62:65]
	v_mfma_f32_16x16x32_bf16 v[46:49], v[150:153], v[188:191], v[46:49]
	v_mfma_f32_16x16x32_bf16 v[46:49], v[154:157], v[192:195], v[46:49]
	v_mfma_f32_16x16x32_bf16 v[30:33], v[150:153], v[202:205], v[30:33]
	v_mfma_f32_16x16x32_bf16 v[30:33], v[154:157], v[206:209], v[30:33]
	v_mfma_f32_16x16x32_bf16 v[14:17], v[150:153], v[210:213], v[14:17]
	v_mfma_f32_16x16x32_bf16 v[14:17], v[154:157], v[214:217], v[14:17]
	v_mfma_f32_16x16x32_bf16 v[50:53], v[158:161], v[180:183], v[50:53]
	v_mfma_f32_16x16x32_bf16 v[50:53], v[162:165], v[184:187], v[50:53]
	v_mfma_f32_16x16x32_bf16 v[34:37], v[158:161], v[188:191], v[34:37]
	v_mfma_f32_16x16x32_bf16 v[34:37], v[162:165], v[192:195], v[34:37]
	v_mfma_f32_16x16x32_bf16 v[18:21], v[158:161], v[202:205], v[18:21]
	v_mfma_f32_16x16x32_bf16 v[18:21], v[162:165], v[206:209], v[18:21]
	v_mfma_f32_16x16x32_bf16 v[2:5], v[158:161], v[210:213], v[2:5]
	v_mfma_f32_16x16x32_bf16 v[2:5], v[162:165], v[214:217], v[2:5]
	v_mfma_f32_16x16x32_bf16 v[54:57], v[172:175], v[180:183], v[54:57]
	v_mfma_f32_16x16x32_bf16 v[54:57], v[176:179], v[184:187], v[54:57]
	v_mfma_f32_16x16x32_bf16 v[38:41], v[172:175], v[188:191], v[38:41]
	v_mfma_f32_16x16x32_bf16 v[38:41], v[176:179], v[192:195], v[38:41]
	v_mfma_f32_16x16x32_bf16 v[22:25], v[172:175], v[202:205], v[22:25]
	v_mfma_f32_16x16x32_bf16 v[22:25], v[176:179], v[206:209], v[22:25]
	v_mfma_f32_16x16x32_bf16 v[6:9], v[172:175], v[210:213], v[6:9]
	v_mfma_f32_16x16x32_bf16 v[6:9], v[176:179], v[214:217], v[6:9]
	s_setprio 0
	s_barrier
	s_add_i32 s38, 0, 0x18000
	v_add_u32_e32 v0, s38, v167
	s_add_i32 s39, 0, 0x1c000
	ds_read_b128 v[142:145], v0
	ds_read_b128 v[146:149], v0 offset:1024
	ds_read_b128 v[150:153], v0 offset:2048
	ds_read_b128 v[154:157], v0 offset:3072
	v_add_u32_e32 v0, s39, v167
	ds_read_b128 v[158:161], v0
	ds_read_b128 v[162:165], v0 offset:1024
	ds_read_b128 v[172:175], v0 offset:2048
	ds_read_b128 v[176:179], v0 offset:3072
	s_add_u32 s72, s72, 0x40000
	s_addc_u32 s73, s73, 0
	s_mov_b32 m0, s78
	v_lshl_add_u64 v[226:227], s[72:73], 0, v[136:137]
	ds_read_b128 v[180:183], v170 offset:32768
	ds_read_b128 v[184:187], v170 offset:33792
	ds_read_b128 v[188:191], v170 offset:34816
	ds_read_b128 v[192:195], v170 offset:35840
	ds_read_b128 v[202:205], v170 offset:36864
	ds_read_b128 v[206:209], v170 offset:37888
	ds_read_b128 v[210:213], v170 offset:38912
	ds_read_b128 v[214:217], v170 offset:39936
	global_load_lds_dwordx4 v[226:227], off
	v_lshl_add_u64 v[226:227], s[72:73], 0, v[132:133]
	s_mov_b32 m0, s79
	s_nop 0
	global_load_lds_dwordx4 v[226:227], off
	s_waitcnt vmcnt(8)
	s_waitcnt lgkmcnt(0)
	s_barrier
	s_setprio 1
	v_mfma_f32_16x16x32_bf16 v[122:125], v[142:145], v[180:183], v[122:125]
	v_mfma_f32_16x16x32_bf16 v[122:125], v[146:149], v[184:187], v[122:125]
	v_mfma_f32_16x16x32_bf16 v[106:109], v[142:145], v[188:191], v[106:109]
	v_mfma_f32_16x16x32_bf16 v[106:109], v[146:149], v[192:195], v[106:109]
	v_mfma_f32_16x16x32_bf16 v[90:93], v[142:145], v[202:205], v[90:93]
	v_mfma_f32_16x16x32_bf16 v[90:93], v[146:149], v[206:209], v[90:93]
	v_mfma_f32_16x16x32_bf16 v[74:77], v[142:145], v[210:213], v[74:77]
	v_mfma_f32_16x16x32_bf16 v[74:77], v[146:149], v[214:217], v[74:77]
	v_mfma_f32_16x16x32_bf16 v[126:129], v[150:153], v[180:183], v[126:129]
	v_mfma_f32_16x16x32_bf16 v[126:129], v[154:157], v[184:187], v[126:129]
	v_mfma_f32_16x16x32_bf16 v[110:113], v[150:153], v[188:191], v[110:113]
	v_mfma_f32_16x16x32_bf16 v[110:113], v[154:157], v[192:195], v[110:113]
	v_mfma_f32_16x16x32_bf16 v[94:97], v[150:153], v[202:205], v[94:97]
	v_mfma_f32_16x16x32_bf16 v[94:97], v[154:157], v[206:209], v[94:97]
	v_mfma_f32_16x16x32_bf16 v[78:81], v[150:153], v[210:213], v[78:81]
	v_mfma_f32_16x16x32_bf16 v[78:81], v[154:157], v[214:217], v[78:81]
	v_mfma_f32_16x16x32_bf16 v[114:117], v[158:161], v[180:183], v[114:117]
	v_mfma_f32_16x16x32_bf16 v[114:117], v[162:165], v[184:187], v[114:117]
	v_mfma_f32_16x16x32_bf16 v[98:101], v[158:161], v[188:191], v[98:101]
	v_mfma_f32_16x16x32_bf16 v[98:101], v[162:165], v[192:195], v[98:101]
	v_mfma_f32_16x16x32_bf16 v[82:85], v[158:161], v[202:205], v[82:85]
	v_mfma_f32_16x16x32_bf16 v[82:85], v[162:165], v[206:209], v[82:85]
	v_mfma_f32_16x16x32_bf16 v[66:69], v[158:161], v[210:213], v[66:69]
	v_mfma_f32_16x16x32_bf16 v[66:69], v[162:165], v[214:217], v[66:69]
	v_mfma_f32_16x16x32_bf16 v[118:121], v[172:175], v[180:183], v[118:121]
	v_mfma_f32_16x16x32_bf16 v[118:121], v[176:179], v[184:187], v[118:121]
	v_mfma_f32_16x16x32_bf16 v[102:105], v[172:175], v[188:191], v[102:105]
	v_mfma_f32_16x16x32_bf16 v[102:105], v[176:179], v[192:195], v[102:105]
	v_mfma_f32_16x16x32_bf16 v[86:89], v[172:175], v[202:205], v[86:89]
	v_mfma_f32_16x16x32_bf16 v[86:89], v[176:179], v[206:209], v[86:89]
	v_mfma_f32_16x16x32_bf16 v[70:73], v[172:175], v[210:213], v[70:73]
	v_mfma_f32_16x16x32_bf16 v[70:73], v[176:179], v[214:217], v[70:73]
	s_setprio 0
	s_barrier
; #define PG8_STAGE(bufoff, gbase, voff) do { _Pragma("unroll") for (int _i = 0; _i < 2; ++_i) \
;         __builtin_amdgcn_global_load_lds((const unsigned*)((const char*)(gbase) + (voff)[_i]), (PG8_LAS unsigned*)(lds + (bufoff) + ldsw + _i * 8192), 16, 0, 0); } while (0)
; #define PG8_LDA(dst, b, h) do { _Pragma("unroll") for (int m = 0; m < 4; ++m) _Pragma("unroll") for (int k = 0; k < 2; ++k) dst[m][k] = *(const PG8_LAS bf16x8*)(lds + PG8_SA(b, h) + aoff + m * 2048 + k * 1024); } while (0)
; #define PG8_MMA(ai, bj, At, Bt) do { __builtin_amdgcn_s_setprio(1); _Pragma("unroll") for (int m = 0; m < 4; ++m) _Pragma("unroll") for (int n = 0; n < 2; ++n) _Pragma("unroll") for (int k = 0; k < 2; ++k) \
;         acc[ai][bj][m][n] = __builtin_amdgcn_mfma_f32_16x16x32_bf16(Bt[n][k], At[m][k], acc[ai][bj][m][n], 0, 0, 0); __builtin_amdgcn_s_setprio(0); } while (0)
; #define PG8_WAIT_V(n) asm volatile("s_waitcnt vmcnt(" #n ")" ::: "memory")
; #define PG8_WAIT_L(n) asm volatile("s_waitcnt lgkmcnt(" #n ")" ::: "memory")
; #define PG8_BAR __builtin_amdgcn_s_barrier()
; #define PG8_SCHED __builtin_amdgcn_sched_barrier(0)
; template <class Epi, class Sched, bool ALIGN_EPI = false, bool SP2 = false>
; __device__ __forceinline__ void gemm_phase(PG8_LAS unsigned char* lds, const Gemm g, const Sched& S, const Epi& E) {
;     ...
;             PG8_LDA(At, 1, 1); PG8_STAGE(PG8_SB(1, 0), b3, voffB); PG8_STAGE(PG8_SB(1, 1), b3 + hstep, voffB); PG8_STAGE(PG8_SA(1, 0), a3, voffA);
;             PG8_WAIT_V(8); PG8_WAIT_L(0); PG8_BAR; PG8_MMA(1, 0, At, B0); PG8_MMA(1, 1, At, B1); PG8_BAR; PG8_SCHED;
;     ...
;         if constexpr (ALIGN_EPI) { if (wr == 0) PG8_BAR; }
	s_add_i32 s38, s38, s75
	v_lshl_add_u64 v[218:219], v[218:219], 0, s[30:31]
	s_mov_b32 m0, s38
	ds_read_b128 v[180:183], v170 offset:49152
	ds_read_b128 v[184:187], v170 offset:50176
	ds_read_b128 v[188:191], v170 offset:51200
	ds_read_b128 v[192:195], v170 offset:52224
	ds_read_b128 v[202:205], v170 offset:53248
	ds_read_b128 v[206:209], v170 offset:54272
	ds_read_b128 v[210:213], v170 offset:55296
	ds_read_b128 v[214:217], v170 offset:56320
	global_load_lds_dwordx4 v[218:219], off
	s_add_i32 m0, s38, 0x2000
	s_add_u32 s46, s46, 0x40080
	v_lshl_add_u64 v[218:219], v[220:221], 0, s[30:31]
	s_addc_u32 s47, s47, 0
	s_add_i32 s38, s39, s75
	global_load_lds_dwordx4 v[218:219], off
	v_lshl_add_u64 v[218:219], s[46:47], 0, v[134:135]
	s_mov_b32 m0, s38
	s_nop 0
	global_load_lds_dwordx4 v[218:219], off
	v_lshl_add_u64 v[218:219], s[46:47], 0, v[130:131]
	s_add_i32 m0, s38, 0x2000
	s_nop 0
	global_load_lds_dwordx4 v[218:219], off
	v_lshl_add_u64 v[218:219], v[222:223], 0, s[30:31]
	s_mov_b32 m0, s80
	s_nop 0
	global_load_lds_dwordx4 v[218:219], off
	v_lshl_add_u64 v[218:219], v[224:225], 0, s[30:31]
	s_mov_b32 m0, s81
	s_nop 0
	global_load_lds_dwordx4 v[218:219], off
	s_waitcnt vmcnt(8)
	s_waitcnt lgkmcnt(0)
	s_barrier
	s_setprio 1
	v_mfma_f32_16x16x32_bf16 v[58:61], v[142:145], v[180:183], v[58:61]
	v_mfma_f32_16x16x32_bf16 v[58:61], v[146:149], v[184:187], v[58:61]
	v_mfma_f32_16x16x32_bf16 v[42:45], v[142:145], v[188:191], v[42:45]
	v_mfma_f32_16x16x32_bf16 v[42:45], v[146:149], v[192:195], v[42:45]
	v_mfma_f32_16x16x32_bf16 v[26:29], v[142:145], v[202:205], v[26:29]
	v_mfma_f32_16x16x32_bf16 v[26:29], v[146:149], v[206:209], v[26:29]
	v_mfma_f32_16x16x32_bf16 v[10:13], v[142:145], v[210:213], v[10:13]
	v_mfma_f32_16x16x32_bf16 v[10:13], v[146:149], v[214:217], v[10:13]
	v_mfma_f32_16x16x32_bf16 v[62:65], v[150:153], v[180:183], v[62:65]
	v_mfma_f32_16x16x32_bf16 v[62:65], v[154:157], v[184:187], v[62:65]
	v_mfma_f32_16x16x32_bf16 v[46:49], v[150:153], v[188:191], v[46:49]
	v_mfma_f32_16x16x32_bf16 v[46:49], v[154:157], v[192:195], v[46:49]
	v_mfma_f32_16x16x32_bf16 v[30:33], v[150:153], v[202:205], v[30:33]
	v_mfma_f32_16x16x32_bf16 v[30:33], v[154:157], v[206:209], v[30:33]
	v_mfma_f32_16x16x32_bf16 v[14:17], v[150:153], v[210:213], v[14:17]
	v_mfma_f32_16x16x32_bf16 v[14:17], v[154:157], v[214:217], v[14:17]
	s_add_i32 s84, s84, 2
	s_add_u32 s48, s48, 0x100
	s_addc_u32 s49, s49, 0
	s_add_u32 s53, s53, 0x100
	s_addc_u32 s69, s69, 0
	s_cmp_gt_u32 s84, 13
	v_mfma_f32_16x16x32_bf16 v[50:53], v[158:161], v[180:183], v[50:53]
	v_mfma_f32_16x16x32_bf16 v[50:53], v[162:165], v[184:187], v[50:53]
	v_mfma_f32_16x16x32_bf16 v[34:37], v[158:161], v[188:191], v[34:37]
	v_mfma_f32_16x16x32_bf16 v[34:37], v[162:165], v[192:195], v[34:37]
	v_mfma_f32_16x16x32_bf16 v[18:21], v[158:161], v[202:205], v[18:21]
	v_mfma_f32_16x16x32_bf16 v[18:21], v[162:165], v[206:209], v[18:21]
	v_mfma_f32_16x16x32_bf16 v[2:5], v[158:161], v[210:213], v[2:5]
	v_mfma_f32_16x16x32_bf16 v[2:5], v[162:165], v[214:217], v[2:5]
	v_mfma_f32_16x16x32_bf16 v[54:57], v[172:175], v[180:183], v[54:57]
	v_mfma_f32_16x16x32_bf16 v[54:57], v[176:179], v[184:187], v[54:57]
	v_mfma_f32_16x16x32_bf16 v[38:41], v[172:175], v[188:191], v[38:41]
	v_mfma_f32_16x16x32_bf16 v[38:41], v[176:179], v[192:195], v[38:41]
	v_mfma_f32_16x16x32_bf16 v[22:25], v[172:175], v[202:205], v[22:25]
	v_mfma_f32_16x16x32_bf16 v[22:25], v[176:179], v[206:209], v[22:25]
	v_mfma_f32_16x16x32_bf16 v[6:9], v[172:175], v[210:213], v[6:9]
	v_mfma_f32_16x16x32_bf16 v[6:9], v[176:179], v[214:217], v[6:9]
	s_setprio 0
	s_barrier
	s_cbranch_scc0 .LBB0_408
	s_and_b64 vcc, exec, s[64:65]
	s_cbranch_vccz .LBB0_411
	s_barrier
